# v16: + nt on GLA scan/output-pass read-once loads (GKV, GDEC, CUM, GS0, last-use P rows)
# baseline (speedup 1.0000x reference)
.LBB0_2262:
	v_lshl_add_u64 v[10:11], s[38:39], 0, v[8:9]
	v_add_co_u32_e32 v14, vcc, 0x22400000, v10
	v_lshl_add_u64 v[12:13], s[38:39], 0, v[6:7]
	s_nop 0
	v_addc_co_u32_e32 v15, vcc, 0, v11, vcc
	v_add_co_u32_e32 v12, vcc, 0x26400000, v12
	global_load_dword v3, v[14:15], off nt
	s_nop 0
	v_addc_co_u32_e32 v13, vcc, 0, v13, vcc
	v_add_co_u32_e32 v14, vcc, 0x22408000, v10
	global_load_dword v5, v[12:13], off nt
	global_load_dword v40, v[12:13], off offset:256 nt
	global_load_dword v41, v[12:13], off offset:512 nt
	global_load_dword v42, v[12:13], off offset:768 nt
	global_load_dword v43, v[12:13], off offset:1024 nt
	global_load_dword v44, v[12:13], off offset:1280 nt
	global_load_dword v45, v[12:13], off offset:1536 nt
	global_load_dword v46, v[12:13], off offset:1792 nt
	global_load_dword v47, v[12:13], off offset:2048 nt
	global_load_dword v48, v[12:13], off offset:2304 nt
	global_load_dword v49, v[12:13], off offset:2560 nt
	global_load_dword v50, v[12:13], off offset:2816 nt
	global_load_dword v51, v[12:13], off offset:3072 nt
	global_load_dword v52, v[12:13], off offset:3328 nt
	global_load_dword v53, v[12:13], off offset:3584 nt
	v_addc_co_u32_e32 v15, vcc, 0, v11, vcc
	v_add_co_u32_e32 v16, vcc, 0x22410000, v10
	s_add_i32 s2, s2, 16
	s_nop 0
	v_addc_co_u32_e32 v17, vcc, 0, v11, vcc
	v_add_co_u32_e32 v18, vcc, 0x22418000, v10
	global_load_dword v54, v[14:15], off nt
	global_load_dword v55, v[16:17], off nt
	v_addc_co_u32_e32 v19, vcc, 0, v11, vcc
	v_add_co_u32_e32 v14, vcc, 0x22420000, v10
	v_lshl_add_u64 v[6:7], v[6:7], 0, s[8:9]
	s_nop 0
	v_addc_co_u32_e32 v15, vcc, 0, v11, vcc
	v_add_co_u32_e32 v16, vcc, 0x22428000, v10
	global_load_dword v56, v[18:19], off nt
	global_load_dword v57, v[14:15], off nt
	v_addc_co_u32_e32 v17, vcc, 0, v11, vcc
	v_add_co_u32_e32 v14, vcc, 0x22430000, v10
	v_lshl_add_u64 v[8:9], v[8:9], 0, s[10:11]
	s_nop 0
	v_addc_co_u32_e32 v15, vcc, 0, v11, vcc
	v_add_co_u32_e32 v18, vcc, 0x22438000, v10
	global_load_dword v58, v[16:17], off nt
	global_load_dword v59, v[14:15], off nt
	v_addc_co_u32_e32 v19, vcc, 0, v11, vcc
	v_add_co_u32_e32 v14, vcc, 0x22440000, v10
	global_load_dword v60, v[18:19], off nt
	global_load_dword v61, v[12:13], off offset:3840 nt
	v_addc_co_u32_e32 v15, vcc, 0, v11, vcc
	v_add_co_u32_e32 v16, vcc, 0x22448000, v10
	s_cmpk_lt_u32 s2, 0x70
	s_nop 0
	v_addc_co_u32_e32 v17, vcc, 0, v11, vcc
	v_add_co_u32_e32 v12, vcc, 0x22450000, v10
	global_load_dword v62, v[14:15], off nt
	global_load_dword v63, v[16:17], off nt
	v_addc_co_u32_e32 v13, vcc, 0, v11, vcc
	v_add_co_u32_e32 v14, vcc, 0x22458000, v10
	s_waitcnt vmcnt(0) lgkmcnt(0)
	v_fmac_f32_e32 v3, v1, v5
	v_addc_co_u32_e32 v15, vcc, 0, v11, vcc
	v_add_co_u32_e32 v16, vcc, 0x22460000, v10
	global_load_dword v64, v[12:13], off nt
	global_load_dword v65, v[14:15], off nt
	v_addc_co_u32_e32 v17, vcc, 0, v11, vcc
	v_add_co_u32_e32 v12, vcc, 0x22468000, v10
	v_fmac_f32_e32 v54, v3, v40
	s_nop 0
	v_addc_co_u32_e32 v13, vcc, 0, v11, vcc
	v_add_co_u32_e32 v14, vcc, 0x22470000, v10
	global_load_dword v66, v[16:17], off nt
	global_load_dword v67, v[12:13], off nt
	v_addc_co_u32_e32 v15, vcc, 0, v11, vcc
	v_add_co_u32_e32 v12, vcc, 0x22478000, v10
	v_fmac_f32_e32 v55, v54, v41
	s_nop 0
	v_addc_co_u32_e32 v13, vcc, 0, v11, vcc
	global_load_dword v68, v[14:15], off nt
	global_load_dword v69, v[12:13], off nt
	v_add_co_u32_e32 v16, vcc, 0x24400000, v10
	v_fmac_f32_e32 v56, v55, v42
	s_nop 0
	v_addc_co_u32_e32 v17, vcc, 0, v11, vcc
	v_add_co_u32_e32 v12, vcc, 0x24408000, v10
	global_store_dword v[16:17], v1, off
	s_nop 0
	v_addc_co_u32_e32 v13, vcc, 0, v11, vcc
	v_add_co_u32_e32 v14, vcc, 0x24410000, v10
	v_fmac_f32_e32 v57, v56, v43
	s_nop 0
	v_addc_co_u32_e32 v15, vcc, 0, v11, vcc
	v_add_co_u32_e32 v16, vcc, 0x24418000, v10
	v_fmac_f32_e32 v58, v57, v44
	s_nop 0
	v_addc_co_u32_e32 v17, vcc, 0, v11, vcc
	v_add_co_u32_e32 v18, vcc, 0x24420000, v10
	v_fmac_f32_e32 v59, v58, v45
	s_nop 0
	v_addc_co_u32_e32 v19, vcc, 0, v11, vcc
	v_add_co_u32_e32 v20, vcc, 0x24428000, v10
	v_fmac_f32_e32 v60, v59, v46
	s_nop 0
	v_addc_co_u32_e32 v21, vcc, 0, v11, vcc
	v_add_co_u32_e32 v22, vcc, 0x24430000, v10
	v_fmac_f32_e32 v62, v60, v47
	s_nop 0
	v_addc_co_u32_e32 v23, vcc, 0, v11, vcc
	v_add_co_u32_e32 v24, vcc, 0x24438000, v10
	v_fmac_f32_e32 v63, v62, v48
	s_nop 0
	v_addc_co_u32_e32 v25, vcc, 0, v11, vcc
	v_add_co_u32_e32 v26, vcc, 0x24440000, v10
	global_store_dword v[12:13], v3, off
	s_nop 0
	v_addc_co_u32_e32 v27, vcc, 0, v11, vcc
	v_add_co_u32_e32 v28, vcc, 0x24448000, v10
	global_store_dword v[14:15], v54, off
	s_nop 0
	v_addc_co_u32_e32 v29, vcc, 0, v11, vcc
	v_add_co_u32_e32 v30, vcc, 0x24450000, v10
	global_store_dword v[16:17], v55, off
	s_nop 0
	v_addc_co_u32_e32 v31, vcc, 0, v11, vcc
	v_add_co_u32_e32 v32, vcc, 0x24458000, v10
	s_waitcnt vmcnt(0) lgkmcnt(0)
	v_fmac_f32_e32 v64, v63, v49
	v_addc_co_u32_e32 v33, vcc, 0, v11, vcc
	v_add_co_u32_e32 v34, vcc, 0x24460000, v10
	v_fmac_f32_e32 v65, v64, v50
	s_nop 0
	v_addc_co_u32_e32 v35, vcc, 0, v11, vcc
	v_add_co_u32_e32 v36, vcc, 0x24468000, v10
	global_store_dword v[18:19], v56, off
	s_nop 0
	v_addc_co_u32_e32 v37, vcc, 0, v11, vcc
	v_add_co_u32_e32 v38, vcc, 0x24470000, v10
	v_fmac_f32_e32 v66, v65, v51
	s_nop 0
	v_addc_co_u32_e32 v39, vcc, 0, v11, vcc
	v_fmac_f32_e32 v67, v66, v52
	v_add_co_u32_e32 v10, vcc, 0x24478000, v10
	v_fmac_f32_e32 v68, v67, v53
	v_mov_b32_e32 v1, v69
	v_addc_co_u32_e32 v11, vcc, 0, v11, vcc
	v_fmac_f32_e32 v1, v68, v61
	global_store_dword v[20:21], v57, off
	global_store_dword v[22:23], v58, off
	global_store_dword v[24:25], v59, off
	global_store_dword v[26:27], v60, off
	global_store_dword v[28:29], v62, off
	global_store_dword v[30:31], v63, off
	global_store_dword v[32:33], v64, off
	global_store_dword v[34:35], v65, off
	global_store_dword v[36:37], v66, off
	global_store_dword v[38:39], v67, off
	global_store_dword v[10:11], v68, off
	s_cbranch_scc1 .LBB0_2262
	v_ashrrev_i32_e32 v5, 31, v4
	v_readlane_b32 s4, v228, 4
	v_lshlrev_b64 v[4:5], 15, v[4:5]
	v_readlane_b32 s5, v228, 5
	v_lshlrev_b32_e32 v2, 2, v2
	v_mov_b32_e32 v3, 0
	v_lshl_add_u64 v[4:5], s[4:5], 0, v[4:5]
	v_lshl_add_u64 v[2:3], v[4:5], 0, v[2:3]
	v_add_co_u32_e32 v2, vcc, 0x8280000, v2
	s_nop 1
	v_addc_co_u32_e32 v3, vcc, 0, v3, vcc
	global_store_dword v[2:3], v1, off

.LBB0_2283:
	s_and_b64 vcc, exec, s[6:7]
	s_cbranch_vccz .LBB0_2895
	s_add_u32 s5, s66, s81
	s_addc_u32 s6, s67, s80
	s_add_u32 s18, s5, 0x16000000
	s_movk_i32 s5, 0x100
	v_and_b32_e32 v1, 63, v138
	s_addc_u32 s19, s6, 0
	v_cmp_gt_i32_e32 vcc, s5, v138
	s_barrier
	s_and_saveexec_b64 s[6:7], vcc
	s_cbranch_execz .LBB0_2286
	v_and_b32_e32 v2, 0xffffffc0, v138
	v_readlane_b32 s5, v228, 22
	s_nop 1
	v_add_u32_e32 v2, s5, v2
	v_or_b32_e32 v2, v2, v1
	v_ashrrev_i32_e32 v3, 31, v2
	v_lshl_add_u64 v[2:3], v[2:3], 2, s[18:19]
	global_load_dword v2, v[2:3], off nt
	v_lshl_add_u32 v3, v138, 2, s36
	s_waitcnt vmcnt(0) lgkmcnt(0)
	v_mul_f32_e32 v2, 0x3e000000, v2
	ds_write_b32 v3, v2

.LBB0_2293:
	s_add_u32 s6, s66, s86
	s_addc_u32 s7, s67, s87
	s_lshl_b32 s52, s85, 2
	s_add_u32 s8, s6, s52
	s_addc_u32 s9, s7, 0
	v_lshlrev_b32_e32 v102, 2, v1
	v_mov_b32_e32 v103, v99
	s_lshl_b32 s6, s5, 4
	v_lshl_add_u64 v[2:3], s[8:9], 0, v[102:103]
	s_mov_b64 s[8:9], 0x6600000
	v_lshl_add_u64 v[2:3], v[2:3], 0, s[8:9]
	v_mov_b32_e32 v19, 0
	s_cmp_gt_i32 s5, 7
	v_mov_b32_e32 v10, 0
	s_waitcnt lgkmcnt(0)
	s_barrier
	s_cbranch_scc1 .LBB0_2295
	s_ashr_i32 s7, s6, 31
	s_lshl_b64 s[8:9], s[6:7], 9
	v_lshl_add_u64 v[4:5], v[2:3], 0, s[8:9]
	global_load_dword v10, v[4:5], off nt
.LBB0_2295:
	s_or_b32 s8, s6, 1
	s_cmpk_gt_i32 s8, 0x7e
	s_cbranch_scc1 .LBB0_2297
	s_ashr_i32 s9, s8, 31
	s_lshl_b64 s[8:9], s[8:9], 9
	v_lshl_add_u64 v[4:5], v[2:3], 0, s[8:9]
	global_load_dword v19, v[4:5], off nt
.LBB0_2297:
	s_or_b32 s8, s6, 2
	v_mov_b32_e32 v17, 0
	s_cmpk_gt_i32 s8, 0x7e
	v_mov_b32_e32 v20, 0
	s_cbranch_scc1 .LBB0_2299
	s_ashr_i32 s9, s8, 31
	s_lshl_b64 s[8:9], s[8:9], 9
	v_lshl_add_u64 v[4:5], v[2:3], 0, s[8:9]
	global_load_dword v20, v[4:5], off nt
.LBB0_2299:
	s_or_b32 s8, s6, 3
	s_cmpk_gt_i32 s8, 0x7e
	s_cbranch_scc1 .LBB0_2301
	s_ashr_i32 s9, s8, 31
	s_lshl_b64 s[8:9], s[8:9], 9
	v_lshl_add_u64 v[4:5], v[2:3], 0, s[8:9]
	global_load_dword v17, v[4:5], off nt
.LBB0_2301:
	s_or_b32 s8, s6, 4
	v_mov_b32_e32 v15, 0
	s_cmpk_gt_i32 s8, 0x7e
	v_mov_b32_e32 v18, 0
	s_cbranch_scc1 .LBB0_2303
	s_ashr_i32 s9, s8, 31
	s_lshl_b64 s[8:9], s[8:9], 9
	v_lshl_add_u64 v[4:5], v[2:3], 0, s[8:9]
	global_load_dword v18, v[4:5], off nt
.LBB0_2303:
	s_or_b32 s8, s6, 5
	s_cmpk_gt_i32 s8, 0x7e
	s_cbranch_scc1 .LBB0_2305
	s_ashr_i32 s9, s8, 31
	s_lshl_b64 s[8:9], s[8:9], 9
	v_lshl_add_u64 v[4:5], v[2:3], 0, s[8:9]
	global_load_dword v15, v[4:5], off nt
.LBB0_2305:
	s_or_b32 s8, s6, 6
	v_mov_b32_e32 v13, 0
	s_cmpk_gt_i32 s8, 0x7e
	v_mov_b32_e32 v16, 0
	s_cbranch_scc1 .LBB0_2307
	s_ashr_i32 s9, s8, 31
	s_lshl_b64 s[8:9], s[8:9], 9
	v_lshl_add_u64 v[4:5], v[2:3], 0, s[8:9]
	global_load_dword v16, v[4:5], off nt
.LBB0_2307:
	s_or_b32 s8, s6, 7
	s_cmpk_gt_i32 s8, 0x7e
	s_cbranch_scc1 .LBB0_2309
	s_ashr_i32 s9, s8, 31
	s_lshl_b64 s[8:9], s[8:9], 9
	v_lshl_add_u64 v[4:5], v[2:3], 0, s[8:9]
	global_load_dword v13, v[4:5], off nt
.LBB0_2309:
	s_or_b32 s8, s6, 8
	v_mov_b32_e32 v11, 0
	s_cmpk_gt_i32 s8, 0x7e
	v_mov_b32_e32 v14, 0
	s_cbranch_scc1 .LBB0_2311
	s_ashr_i32 s9, s8, 31
	s_lshl_b64 s[8:9], s[8:9], 9
	v_lshl_add_u64 v[4:5], v[2:3], 0, s[8:9]
	global_load_dword v14, v[4:5], off nt
.LBB0_2311:
	s_or_b32 s8, s6, 9
	s_cmpk_gt_i32 s8, 0x7e
	s_cbranch_scc1 .LBB0_2313
	s_ashr_i32 s9, s8, 31
	s_lshl_b64 s[8:9], s[8:9], 9
	v_lshl_add_u64 v[4:5], v[2:3], 0, s[8:9]
	global_load_dword v11, v[4:5], off nt
.LBB0_2313:
	s_or_b32 s8, s6, 10
	v_mov_b32_e32 v7, 0
	s_cmpk_gt_i32 s8, 0x7e
	v_mov_b32_e32 v12, 0
	s_cbranch_scc1 .LBB0_2315
	s_ashr_i32 s9, s8, 31
	s_lshl_b64 s[8:9], s[8:9], 9
	v_lshl_add_u64 v[4:5], v[2:3], 0, s[8:9]
	global_load_dword v12, v[4:5], off nt
.LBB0_2315:
	s_or_b32 s8, s6, 11
	s_cmpk_gt_i32 s8, 0x7e
	s_cbranch_scc1 .LBB0_2317
	s_ashr_i32 s9, s8, 31
	s_lshl_b64 s[8:9], s[8:9], 9
	v_lshl_add_u64 v[4:5], v[2:3], 0, s[8:9]
	global_load_dword v7, v[4:5], off nt
.LBB0_2317:
	s_or_b32 s8, s6, 12
	v_mov_b32_e32 v4, 0
	s_cmpk_gt_i32 s8, 0x7e
	v_mov_b32_e32 v8, 0
	s_cbranch_scc1 .LBB0_2319
	s_ashr_i32 s9, s8, 31
	s_lshl_b64 s[8:9], s[8:9], 9
	v_lshl_add_u64 v[8:9], v[2:3], 0, s[8:9]
	global_load_dword v8, v[8:9], off nt
.LBB0_2319:
	s_or_b32 s8, s6, 13
	s_cmpk_gt_i32 s8, 0x7e
	s_cbranch_scc1 .LBB0_2321
	s_ashr_i32 s9, s8, 31
	s_lshl_b64 s[8:9], s[8:9], 9
	v_lshl_add_u64 v[4:5], v[2:3], 0, s[8:9]
	global_load_dword v4, v[4:5], off nt
.LBB0_2321:
	s_or_b32 s8, s6, 14
	v_mov_b32_e32 v5, 0
	s_cmpk_gt_i32 s8, 0x7e
	v_mov_b32_e32 v6, 0
	s_cbranch_scc1 .LBB0_2323
	s_ashr_i32 s9, s8, 31
	s_lshl_b64 s[8:9], s[8:9], 9
	v_lshl_add_u64 v[22:23], v[2:3], 0, s[8:9]
	global_load_dword v6, v[22:23], off nt
.LBB0_2323:
	s_or_b32 s6, s6, 15
	s_cmpk_gt_i32 s6, 0x7e
	s_cbranch_scc1 .LBB0_2325
	s_ashr_i32 s7, s6, 31
	s_lshl_b64 s[6:7], s[6:7], 9
	v_lshl_add_u64 v[2:3], v[2:3], 0, s[6:7]
	global_load_dword v5, v[2:3], off nt

.LBB0_2957:
	s_or_b64 exec, exec, s[76:77]
	s_lshl_b32 s9, s8, 4
	s_lshl_b32 s36, s8, 6
	s_and_b32 s9, s9, 0xffffe000
	s_and_b32 s36, s36, 0x1fc0
	s_or_b32 s36, s9, s36
	s_ashr_i32 s9, s8, 31
	s_bfe_u32 s35, s8, 0x20007
	s_lshl_b64 s[44:45], s[8:9], 14
	s_lshl_b32 s37, s35, 6
	v_add_u32_e32 v2, s36, v67
	v_mov_b64_e32 v[26:27], s[12:13]
	v_lshl_add_u64 v[4:5], v[56:57], 0, s[44:45]
	v_add_u32_e32 v10, s36, v68
	v_mad_i64_i32 v[2:3], s[76:77], v2, s29, v[26:27]
	v_add_lshl_u32 v42, v55, s37, 2
	v_add_lshl_u32 v8, v66, s37, 2
	v_mov_b32_e32 v9, v43
	v_mad_i64_i32 v[10:11], s[44:45], v10, s29, v[26:27]
	v_add_co_u32_e32 v14, vcc, s30, v4
	v_lshl_add_u64 v[6:7], v[2:3], 0, v[42:43]
	v_lshl_add_u64 v[2:3], v[2:3], 0, v[8:9]
	v_lshl_add_u64 v[12:13], v[10:11], 0, v[42:43]
	v_lshl_add_u64 v[10:11], v[10:11], 0, v[8:9]
	v_addc_co_u32_e32 v15, vcc, 0, v5, vcc
	global_load_dword v34, v[4:5], off nt
	global_load_dword v35, v[6:7], off nt
	global_load_dword v36, v[2:3], off nt
	global_load_dword v37, v[12:13], off nt
	global_load_dword v38, v[10:11], off nt
	global_load_dword v39, v[14:15], off nt
	global_load_dword v40, v[14:15], off offset:2048 nt
	global_load_dword v41, v[4:5], off offset:2048 nt
	v_add_u32_e32 v2, s36, v69
	v_mad_i64_i32 v[2:3], s[44:45], v2, s29, v[26:27]
	v_add_u32_e32 v10, s36, v70
	v_add_u32_e32 v14, s36, v71
	v_lshl_add_u64 v[6:7], v[2:3], 0, v[42:43]
	v_mad_i64_i32 v[10:11], s[44:45], v10, s29, v[26:27]
	v_mad_i64_i32 v[14:15], s[44:45], v14, s29, v[26:27]
	v_add_co_u32_e32 v16, vcc, s4, v4
	v_lshl_add_u64 v[2:3], v[2:3], 0, v[8:9]
	v_lshl_add_u64 v[12:13], v[10:11], 0, v[42:43]
	v_lshl_add_u64 v[10:11], v[10:11], 0, v[8:9]
	v_addc_co_u32_e32 v17, vcc, 0, v5, vcc
	v_lshl_add_u64 v[18:19], v[14:15], 0, v[42:43]
	v_lshl_add_u64 v[14:15], v[14:15], 0, v[8:9]
	global_load_dword v60, v[6:7], off nt
	global_load_dword v61, v[2:3], off nt
	global_load_dword v62, v[12:13], off nt
	global_load_dword v63, v[10:11], off nt
	global_load_dword v64, v[16:17], off nt
	global_load_dword v65, v[18:19], off nt
	global_load_dword v106, v[14:15], off nt
	global_load_dword v107, v[16:17], off offset:2048 nt
	v_add_u32_e32 v20, s36, v72
	v_mad_i64_i32 v[20:21], s[44:45], v20, s29, v[26:27]
	v_add_u32_e32 v10, s36, v73
	v_add_u32_e32 v14, s36, v74
	v_lshl_add_u64 v[2:3], v[20:21], 0, v[42:43]
	v_mad_i64_i32 v[10:11], s[44:45], v10, s29, v[26:27]
	v_add_co_u32_e32 v4, vcc, s29, v4
	v_mad_i64_i32 v[14:15], s[44:45], v14, s29, v[26:27]
	v_lshl_add_u64 v[6:7], v[20:21], 0, v[8:9]
	v_addc_co_u32_e32 v5, vcc, 0, v5, vcc
	v_lshl_add_u64 v[12:13], v[10:11], 0, v[42:43]
	v_lshl_add_u64 v[10:11], v[10:11], 0, v[8:9]
	v_lshl_add_u64 v[16:17], v[14:15], 0, v[42:43]
	v_lshl_add_u64 v[8:9], v[14:15], 0, v[8:9]
	global_load_dword v42, v[2:3], off nt
	global_load_dword v108, v[6:7], off nt
	global_load_dword v109, v[4:5], off nt
	global_load_dword v110, v[12:13], off nt
	global_load_dword v111, v[10:11], off nt
	global_load_dword v112, v[16:17], off nt
	global_load_dword v113, v[8:9], off nt
	global_load_dword v114, v[4:5], off offset:2048 nt
	s_lshl_b64 s[8:9], s[8:9], 15
	v_add_u32_e32 v2, s36, v75
	v_lshl_add_u64 v[28:29], v[44:45], 0, s[8:9]
	v_mad_i64_i32 v[2:3], s[8:9], v2, s29, v[26:27]
	s_lshl_b32 s70, s35, 9
	v_lshl_add_u64 v[2:3], v[2:3], 0, s[70:71]
	v_mov_b32_e32 v59, v43
	v_add_u32_e32 v10, s36, v76
	v_lshl_add_u64 v[2:3], v[2:3], 0, v[58:59]
	v_mad_i64_i32 v[10:11], s[8:9], v10, s29, v[26:27]
	v_add_co_u32_e32 v2, vcc, s30, v2
	v_lshl_add_u64 v[10:11], v[10:11], 0, s[70:71]
	v_add_u32_e32 v18, s36, v77
	v_addc_co_u32_e32 v3, vcc, 0, v3, vcc
	v_lshl_add_u64 v[10:11], v[10:11], 0, v[58:59]
	v_mad_i64_i32 v[18:19], s[8:9], v18, s29, v[26:27]
	v_add_co_u32_e32 v10, vcc, s30, v10
	v_lshl_add_u64 v[18:19], v[18:19], 0, s[70:71]
	v_add_u32_e32 v30, s36, v78
	v_addc_co_u32_e32 v11, vcc, 0, v11, vcc
	v_lshl_add_u64 v[18:19], v[18:19], 0, v[58:59]
	v_mad_i64_i32 v[26:27], s[8:9], v30, s29, v[26:27]
	v_add_co_u32_e32 v18, vcc, s30, v18
	v_lshl_add_u64 v[26:27], v[26:27], 0, s[70:71]
	s_nop 0
	v_addc_co_u32_e32 v19, vcc, 0, v19, vcc
	v_lshl_add_u64 v[26:27], v[26:27], 0, v[58:59]
	v_add_co_u32_e32 v26, vcc, s30, v26
	v_lshl_add_u64 v[6:7], v[46:47], 2, v[28:29]
	v_lshl_add_u64 v[14:15], v[48:49], 2, v[28:29]
	v_lshl_add_u64 v[22:23], v[50:51], 2, v[28:29]
	v_addc_co_u32_e32 v27, vcc, 0, v27, vcc
	v_lshl_add_u64 v[30:31], v[52:53], 2, v[28:29]
	global_load_dwordx4 v[2:5], v[2:3], off offset:3168 nt
	s_nop 0
	global_load_dwordx4 v[6:9], v[6:7], off nt
	s_nop 0
	global_load_dwordx4 v[10:13], v[10:11], off offset:3168 nt
	s_nop 0
	global_load_dwordx4 v[14:17], v[14:15], off nt
	s_nop 0
	global_load_dwordx4 v[18:21], v[18:19], off offset:3168 nt
	s_nop 0
	global_load_dwordx4 v[22:25], v[22:23], off nt
	s_nop 0
	global_load_dwordx4 v[26:29], v[26:27], off offset:3168 nt
	s_nop 0
	global_load_dwordx4 v[30:33], v[30:31], off nt
	s_waitcnt vmcnt(0) lgkmcnt(0)
	v_mul_f32_e32 v59, 0x3fb8aa3b, v34
	v_mul_f32_e32 v34, 0xbfb8aa3b, v34
	v_exp_f32_e32 v34, v34
	v_exp_f32_e32 v59, v59
	v_mul_f32_e32 v35, 0x3e000000, v35
	v_mul_f32_e32 v34, v36, v34
	v_mul_f32_e32 v36, 0x3fb8aa3b, v41
	v_exp_f32_e32 v36, v36
	v_mul_f32_e32 v35, v35, v59
	v_mul_f32_e32 v41, 0xbfb8aa3b, v41
	s_barrier
	v_exp_f32_e32 v41, v41
	ds_write2st64_b32 v79, v35, v34 offset0:65 offset1:130
	v_mul_f32_e32 v34, 0x3e000000, v37
	v_mul_f32_e32 v34, v34, v36
	v_mul_f32_e32 v36, 0x3fb8aa3b, v39
	v_mul_f32_e32 v37, 0xbfb8aa3b, v39
	v_exp_f32_e32 v36, v36
	v_exp_f32_e32 v37, v37
	v_mul_f32_e32 v35, v38, v41
	ds_write2st64_b32 v80, v34, v35 offset0:65 offset1:130
	v_mul_f32_e32 v34, 0x3e000000, v60
	v_mul_f32_e32 v34, v34, v36
	v_mul_f32_e32 v35, v61, v37
	v_mul_f32_e32 v36, 0x3fb8aa3b, v40
	v_mul_f32_e32 v37, 0xbfb8aa3b, v40
	v_exp_f32_e32 v36, v36
	v_exp_f32_e32 v37, v37
	ds_write2st64_b32 v81, v34, v35 offset0:65 offset1:130
	v_mul_f32_e32 v34, 0x3e000000, v62
	v_mul_f32_e32 v34, v34, v36
	v_mul_f32_e32 v35, v63, v37
	v_mul_f32_e32 v36, 0x3fb8aa3b, v64
	v_mul_f32_e32 v37, 0xbfb8aa3b, v64
	v_exp_f32_e32 v36, v36
	v_exp_f32_e32 v37, v37
	ds_write2st64_b32 v82, v34, v35 offset0:65 offset1:130
	v_mul_f32_e32 v34, 0x3e000000, v65
	v_mul_f32_e32 v34, v34, v36
	v_mul_f32_e32 v35, v106, v37
	v_mul_f32_e32 v36, 0x3fb8aa3b, v107
	v_mul_f32_e32 v37, 0xbfb8aa3b, v107
	v_exp_f32_e32 v36, v36
	v_exp_f32_e32 v37, v37
	ds_write2st64_b32 v83, v34, v35 offset0:65 offset1:130
	v_mul_f32_e32 v34, 0x3e000000, v42
	v_mul_f32_e32 v34, v34, v36
	v_mul_f32_e32 v35, v108, v37
	v_mul_f32_e32 v36, 0x3fb8aa3b, v109
	v_mul_f32_e32 v37, 0xbfb8aa3b, v109
	v_exp_f32_e32 v36, v36
	v_exp_f32_e32 v37, v37
	ds_write2st64_b32 v84, v34, v35 offset0:65 offset1:130
	v_mul_f32_e32 v34, 0x3e000000, v110
	v_mul_f32_e32 v34, v34, v36
	v_mul_f32_e32 v35, v111, v37
	v_mul_f32_e32 v36, 0x3fb8aa3b, v114
	v_mul_f32_e32 v37, 0xbfb8aa3b, v114
	v_exp_f32_e32 v36, v36
	v_exp_f32_e32 v37, v37
	ds_write2st64_b32 v85, v34, v35 offset0:65 offset1:130
	v_mul_f32_e32 v34, 0x3e000000, v112
	v_mul_f32_e32 v34, v34, v36
	v_mul_f32_e32 v35, v113, v37
	ds_write2st64_b32 v86, v34, v35 offset0:65 offset1:130
	ds_write_b128 v87, v[2:5] offset:49920
	ds_write_b128 v88, v[6:9]
	ds_write_b128 v87, v[10:13] offset:58112
	ds_write_b128 v89, v[14:17]
	ds_write_b128 v90, v[18:21]
	ds_write_b128 v91, v[22:25]
	ds_write_b128 v92, v[26:29]
	ds_write_b128 v93, v[30:33]
	v_mov_b32_e32 v2, 0
	s_lshl_b32 s35, s35, 7
	s_mov_b32 s8, 32
	v_mov_b32_e32 v18, v97
	v_mov_b32_e32 v19, v96
	v_mov_b32_e32 v3, v2
	v_mov_b32_e32 v4, v2
	v_mov_b32_e32 v5, v2
	v_mov_b32_e32 v6, v2
	v_mov_b32_e32 v7, v2
	v_mov_b32_e32 v8, v2
	v_mov_b32_e32 v9, v2
	v_mov_b32_e32 v10, v2
	v_mov_b32_e32 v11, v2
	v_mov_b32_e32 v12, v2
	v_mov_b32_e32 v13, v2
	v_mov_b32_e32 v14, v2
	v_mov_b32_e32 v15, v2
	v_mov_b32_e32 v16, v2
	v_mov_b32_e32 v17, v2
	s_waitcnt lgkmcnt(0)
	s_barrier

.LBB0_2965:
	ds_read2_b32 v[20:21], v18 offset1:2
	ds_read2st64_b32 v[22:23], v19 offset1:4
	s_add_i32 s8, s8, -8
	s_cmp_eq_u32 s8, 0
	s_waitcnt lgkmcnt(0)
	v_mfma_f32_32x32x2_f32 v[2:17], v20, v22, v[2:17]
	v_mfma_f32_32x32x2_f32 v[2:17], v21, v23, v[2:17]
	ds_read2_b32 v[20:21], v18 offset0:4 offset1:6
	ds_read2st64_b32 v[22:23], v19 offset0:8 offset1:12
	s_waitcnt lgkmcnt(0)
	v_mfma_f32_32x32x2_f32 v[2:17], v20, v22, v[2:17]
	v_mfma_f32_32x32x2_f32 v[2:17], v21, v23, v[2:17]
	ds_read2_b32 v[20:21], v18 offset0:8 offset1:10
	ds_read2st64_b32 v[22:23], v19 offset0:16 offset1:20
	s_waitcnt lgkmcnt(0)
	v_mfma_f32_32x32x2_f32 v[2:17], v20, v22, v[2:17]
	v_mfma_f32_32x32x2_f32 v[2:17], v21, v23, v[2:17]
	ds_read2_b32 v[20:21], v18 offset0:12 offset1:14
	ds_read2st64_b32 v[22:23], v19 offset0:24 offset1:28
	v_add_u32_e32 v19, 0x2000, v19
	v_add_u32_e32 v18, 64, v18
	s_waitcnt lgkmcnt(0)
	v_mfma_f32_32x32x2_f32 v[2:17], v20, v22, v[2:17]
	v_mfma_f32_32x32x2_f32 v[2:17], v21, v23, v[2:17]
	s_cbranch_scc0 .LBB0_2965
	v_add_u32_e32 v18, 0xc200, v103
	s_barrier
	s_nop 14
	ds_write2_b32 v18, v2, v3 offset0:64 offset1:196
	v_add_u32_e32 v2, 0xc600, v103
	ds_write2_b32 v2, v4, v5 offset0:72 offset1:204
	v_add_u32_e32 v2, 0xd200, v103
	ds_write2_b32 v2, v6, v7 offset0:96 offset1:228
	v_add_u32_e32 v2, 0xd600, v103
	ds_write2_b32 v2, v8, v9 offset0:104 offset1:236
	v_add_u32_e32 v2, 0xe400, v103
	ds_write2_b32 v2, v10, v11 offset1:132
	v_add_u32_e32 v2, 0xe800, v103
	ds_write2_b32 v2, v12, v13 offset0:8 offset1:140
	v_add_u32_e32 v2, 0xf400, v103
	ds_write2_b32 v2, v14, v15 offset0:32 offset1:164
	v_add_u32_e32 v2, 0xf800, v103
	v_mov_b64_e32 v[18:19], s[0:1]
	ds_write2_b32 v2, v16, v17 offset0:40 offset1:172
	s_waitcnt lgkmcnt(0)
	s_barrier
	ds_read_b128 v[14:17], v95 offset:49920
	ds_read_b128 v[10:13], v95 offset:49936
	ds_read_b128 v[6:9], v95 offset:49952
	ds_read_b128 v[2:5], v95 offset:49968
	global_load_dwordx2 v[22:23], v[18:19], off offset:168 sc0 sc1
	s_waitcnt vmcnt(0)
	v_add_u32_e32 v60, s36, v94
	v_mov_b64_e32 v[18:19], s[12:13]
	v_and_b32_e32 v21, 64, v166
	s_lshl_b32 s70, s35, 2
	v_mad_i64_i32 v[18:19], s[8:9], v60, s29, v[18:19]
	v_xor_b32_e32 v20, 1, v166
	v_lshlrev_b32_e32 v42, 2, v54
	v_add_u32_e32 v59, 64, v21
	v_lshl_add_u64 v[18:19], v[18:19], 0, s[70:71]
	v_cmp_lt_i32_e32 vcc, v20, v59
	v_lshl_add_u64 v[30:31], v[18:19], 0, v[42:43]
	s_waitcnt lgkmcnt(0)
	v_mov_b32_e32 v26, v15
	v_cndmask_b32_e32 v20, v166, v20, vcc
	v_add_co_u32_e32 v18, vcc, s4, v30
	v_lshlrev_b32_e32 v61, 2, v20
	s_nop 0
	v_addc_co_u32_e32 v19, vcc, 0, v31, vcc
	global_load_dwordx4 v[18:21], v[18:19], off offset:1184 nt
	v_mov_b32_e32 v27, v11
	v_mov_b32_e32 v24, v14
	v_mov_b32_e32 v25, v10
	v_mov_b32_e32 v36, v7
	v_mov_b32_e32 v37, v3
	v_pk_mul_f32 v[26:27], v[26:27], v[26:27]
	v_mov_b32_e32 v28, v16
	v_mov_b32_e32 v29, v12
	v_mov_b32_e32 v34, v6
	v_mov_b32_e32 v35, v2
	v_pk_mul_f32 v[36:37], v[36:37], v[36:37]
	v_pk_fma_f32 v[24:25], v[24:25], v[24:25], v[26:27]
	v_mov_b32_e32 v32, v17
	v_mov_b32_e32 v33, v13
	v_mov_b32_e32 v38, v8
	v_mov_b32_e32 v39, v4
	v_pk_fma_f32 v[26:27], v[34:35], v[34:35], v[36:37]
	v_pk_fma_f32 v[24:25], v[28:29], v[28:29], v[24:25]
	v_mov_b32_e32 v40, v9
	v_mov_b32_e32 v41, v5
	v_pk_fma_f32 v[26:27], v[38:39], v[38:39], v[26:27]
	v_pk_fma_f32 v[24:25], v[32:33], v[32:33], v[24:25]
	v_pk_fma_f32 v[26:27], v[40:41], v[40:41], v[26:27]
	v_add_f32_e32 v24, v24, v25
	v_add_f32_e32 v24, v24, v26
	v_add_f32_e32 v24, v24, v27
	ds_bpermute_b32 v25, v61, v24
	v_xor_b32_e32 v26, 2, v166
	v_cmp_lt_i32_e32 vcc, v26, v59
	v_lshl_add_u64 v[62:63], v[30:31], 0, s[72:73]
	v_mov_b32_e32 v38, v14
	v_cndmask_b32_e32 v26, v166, v26, vcc
	v_lshlrev_b32_e32 v26, 2, v26
	s_waitcnt lgkmcnt(0)
	v_add_f32_e32 v24, v24, v25
	ds_bpermute_b32 v25, v26, v24
	v_ashrrev_i32_e32 v61, 31, v60
	s_lshl_b32 s70, s35, 1
	s_mov_b64 s[76:77], 0
	s_waitcnt lgkmcnt(0)
	v_add_f32_e32 v32, v24, v25
	v_lshl_add_u64 v[64:65], v[22:23], 0, v[42:43]
	global_load_dwordx4 v[26:29], v[64:65], off nt
	v_xor_b32_e32 v22, 4, v166
	v_cmp_lt_i32_e32 vcc, v22, v59
	s_nop 1
	v_cndmask_b32_e32 v22, v166, v22, vcc
	v_lshlrev_b32_e32 v22, 2, v22
	ds_bpermute_b32 v33, v22, v32
	global_load_dwordx4 v[22:25], v[64:65], off offset:16 nt
	s_waitcnt lgkmcnt(0)
	v_add_f32_e32 v30, v32, v33
	v_fmamk_f32 v30, v30, 0x3c000000, v104
	v_mul_f32_e32 v31, 0x4f800000, v30
	v_cmp_gt_f32_e32 vcc, s31, v30
	s_nop 1
	v_cndmask_b32_e32 v39, v30, v31, vcc
	v_sqrt_f32_e32 v40, v39
	global_load_dwordx4 v[30:33], v[62:63], off offset:16 nt
	global_load_dwordx4 v[34:37], v[62:63], off offset:48 nt
	v_add_u32_e32 v14, -1, v40
	v_add_u32_e32 v41, 1, v40
	v_fma_f32 v42, -v14, v40, v39
	v_fma_f32 v59, -v41, v40, v39
	v_cmp_ge_f32_e64 s[8:9], 0, v42
	s_nop 1
	v_cndmask_b32_e64 v14, v40, v14, s[8:9]
	v_cmp_lt_f32_e64 s[8:9], 0, v59
	s_nop 1
	v_cndmask_b32_e64 v14, v14, v41, s[8:9]
	v_mul_f32_e32 v40, 0x37800000, v14
	v_cndmask_b32_e32 v14, v14, v40, vcc
	v_cmp_class_f32_e32 vcc, v39, v105
	s_nop 1
	v_cndmask_b32_e32 v14, v14, v39, vcc
	v_div_scale_f32 v40, s[8:9], v14, v14, 1.0
	v_rcp_f32_e32 v41, v40
	v_mov_b32_e32 v39, v16
	v_div_scale_f32 v16, vcc, 1.0, v14, 1.0
	v_fma_f32 v42, -v40, v41, 1.0
	v_fmac_f32_e32 v41, v42, v41
	v_mul_f32_e32 v42, v16, v41
	v_fma_f32 v59, -v40, v42, v16
	v_fmac_f32_e32 v42, v59, v41
	v_fma_f32 v16, -v40, v42, v16
	v_div_fmas_f32 v16, v16, v41, v42
	v_div_fixup_f32 v14, v16, v14, 1.0
	v_pk_mul_f32 v[110:111], v[38:39], v[14:15] op_sel_hi:[1,0]
	s_waitcnt vmcnt(0)
	v_mul_f32_e32 v16, 0xbfb8aa3b, v18
	v_mul_f32_e32 v38, 0xbfb8aa3b, v20
	v_exp_f32_e32 v112, v16
	v_exp_f32_e32 v113, v38
	v_mul_f32_e32 v16, 0xbfb8aa3b, v19
	global_load_dwordx4 v[38:41], v[64:65], off offset:48 nt
	global_load_dwordx4 v[106:109], v[64:65], off offset:32 nt
	v_exp_f32_e32 v64, v16
	v_pk_add_f32 v[112:113], v[112:113], 1.0 op_sel_hi:[1,0]
	s_nop 0
	v_div_scale_f32 v16, s[8:9], v113, v113, v20
	v_rcp_f32_e32 v65, v16
	v_div_scale_f32 v59, s[8:9], v112, v112, v18
	v_rcp_f32_e32 v116, v59
	v_fma_f32 v114, -v16, v65, 1.0
	v_div_scale_f32 v42, vcc, v20, v113, v20
	v_fmac_f32_e32 v65, v114, v65
	v_fma_f32 v115, -v59, v116, 1.0
	v_mul_f32_e32 v114, v42, v65
	v_fmac_f32_e32 v116, v115, v116
	v_fma_f32 v115, -v16, v114, v42
	v_fmac_f32_e32 v114, v115, v65
	v_fma_f32 v16, -v16, v114, v42
	v_div_fmas_f32 v16, v16, v65, v114
	v_div_scale_f32 v117, s[8:9], v18, v112, v18
	v_div_fixup_f32 v113, v16, v113, v20
	v_mul_f32_e32 v20, 0xbfb8aa3b, v21
	v_mul_f32_e32 v118, v117, v116
	v_exp_f32_e32 v65, v20
	v_fma_f32 v119, -v59, v118, v117
	v_fmac_f32_e32 v118, v119, v116
	v_fma_f32 v16, -v59, v118, v117
	s_mov_b64 vcc, s[8:9]
	v_div_fmas_f32 v16, v16, v116, v118
	v_pk_add_f32 v[64:65], v[64:65], 1.0 op_sel_hi:[1,0]
	v_div_fixup_f32 v112, v16, v112, v18
	v_mov_b32_e32 v16, v15
	v_div_scale_f32 v15, s[8:9], v65, v65, v21
	v_rcp_f32_e32 v18, v15
	v_mov_b32_e32 v114, v26
	v_mov_b32_e32 v115, v28
	v_mov_b32_e32 v28, v27
	v_fma_f32 v20, -v15, v18, 1.0
	v_fmac_f32_e32 v18, v20, v18
	v_div_scale_f32 v20, vcc, v21, v65, v21
	v_mul_f32_e32 v26, v20, v18
	v_fma_f32 v27, -v15, v26, v20
	v_fmac_f32_e32 v26, v27, v18
	v_pk_mul_f32 v[16:17], v[16:17], v[14:15] op_sel_hi:[1,0]
	v_fma_f32 v15, -v15, v26, v20
	v_div_scale_f32 v20, s[8:9], v64, v64, v19
	v_rcp_f32_e32 v27, v20
	v_div_fmas_f32 v15, v15, v18, v26
	v_div_fixup_f32 v21, v15, v65, v21
	v_pk_mul_f32 v[16:17], v[28:29], v[16:17]
	v_fma_f32 v15, -v20, v27, 1.0
	v_fmac_f32_e32 v27, v15, v27
	v_div_scale_f32 v15, vcc, v19, v64, v19
	v_mul_f32_e32 v18, v15, v27
	v_fma_f32 v26, -v20, v18, v15
	v_fmac_f32_e32 v18, v26, v27
	v_fma_f32 v15, -v20, v18, v15
	v_div_fmas_f32 v15, v15, v27, v18
	v_div_fixup_f32 v20, v15, v64, v19
	v_pk_mul_f32 v[20:21], v[20:21], v[16:17]
	global_load_dwordx4 v[16:19], v[62:63], off offset:32 nt
	s_waitcnt lgkmcnt(0)
	v_mul_f32_e32 v15, 0xbfb8aa3b, v30
	v_exp_f32_e32 v26, v15
	v_mul_f32_e32 v15, 0xbfb8aa3b, v31
	v_exp_f32_e32 v28, v15
	v_mul_f32_e32 v15, 0xbfb8aa3b, v32
	v_exp_f32_e32 v27, v15
	v_mov_b32_e32 v62, v10
	v_mov_b32_e32 v63, v12
	v_pk_mul_f32 v[62:63], v[62:63], v[14:15] op_sel_hi:[1,0]
	v_pk_add_f32 v[26:27], v[26:27], 1.0 op_sel_hi:[1,0]
	v_mov_b32_e32 v64, v22
	v_div_scale_f32 v10, s[8:9], v27, v27, v32
	v_rcp_f32_e32 v12, v10
	v_mov_b32_e32 v65, v24
	v_pk_mul_f32 v[110:111], v[114:115], v[110:111]
	v_pk_mul_f32 v[62:63], v[62:63], v[64:65]
	v_fma_f32 v15, -v10, v12, 1.0
	v_fmac_f32_e32 v12, v15, v12
	v_div_scale_f32 v15, vcc, v32, v27, v32
	v_mul_f32_e32 v22, v15, v12
	v_fma_f32 v24, -v10, v22, v15
	v_fmac_f32_e32 v22, v24, v12
	v_fma_f32 v10, -v10, v22, v15
	v_div_scale_f32 v15, s[8:9], v26, v26, v30
	v_rcp_f32_e32 v24, v15
	v_div_fmas_f32 v10, v10, v12, v22
	v_div_fixup_f32 v27, v10, v27, v32
	v_pk_mul_f32 v[110:111], v[112:113], v[110:111]
	v_fma_f32 v10, -v15, v24, 1.0
	v_fmac_f32_e32 v24, v10, v24
	v_div_scale_f32 v10, vcc, v30, v26, v30
	v_mul_f32_e32 v12, v10, v24
	v_fma_f32 v22, -v15, v12, v10
	v_fmac_f32_e32 v12, v22, v24
	v_fma_f32 v10, -v15, v12, v10
	v_div_fmas_f32 v10, v10, v24, v12
	v_mul_f32_e32 v12, 0xbfb8aa3b, v33
	v_exp_f32_e32 v29, v12
	v_div_fixup_f32 v26, v10, v26, v30
	v_mov_b32_e32 v12, v11
	v_mov_b32_e32 v24, v23
	v_pk_add_f32 v[10:11], v[28:29], 1.0 op_sel_hi:[1,0]
	v_pk_mul_f32 v[26:27], v[62:63], v[26:27]
	v_div_scale_f32 v15, s[8:9], v11, v11, v33
	v_rcp_f32_e32 v22, v15
	v_pk_mul_f32 v[12:13], v[12:13], v[14:15] op_sel_hi:[1,0]
	v_lshlrev_b32_e32 v42, 1, v54
	v_pk_mul_f32 v[12:13], v[12:13], v[24:25]
	v_fma_f32 v23, -v15, v22, 1.0
	v_fmac_f32_e32 v22, v23, v22
	v_div_scale_f32 v23, vcc, v33, v11, v33
	v_mul_f32_e32 v24, v23, v22
	v_fma_f32 v25, -v15, v24, v23
	v_fmac_f32_e32 v24, v25, v22
	v_fma_f32 v15, -v15, v24, v23
	v_div_scale_f32 v23, s[8:9], v10, v10, v31
	v_rcp_f32_e32 v25, v23
	v_div_fmas_f32 v15, v15, v22, v24
	v_div_fixup_f32 v11, v15, v11, v33
	v_fma_f32 v15, -v23, v25, 1.0
	v_fmac_f32_e32 v25, v15, v25
	v_div_scale_f32 v15, vcc, v31, v10, v31
	v_mul_f32_e32 v22, v15, v25
	v_fma_f32 v24, -v23, v22, v15
	v_fmac_f32_e32 v22, v24, v25
	v_fma_f32 v15, -v23, v22, v15
	v_div_fmas_f32 v15, v15, v25, v22
	v_div_fixup_f32 v10, v15, v10, v31
	v_pk_mul_f32 v[10:11], v[12:13], v[10:11]
	v_cvt_pk_bf16_f32 v13, v27, v11
	v_cvt_pk_bf16_f32 v11, v111, v21
	s_waitcnt vmcnt(0)
	v_mul_f32_e32 v15, 0xbfb8aa3b, v16
	v_cvt_pk_bf16_f32 v12, v26, v10
	v_cvt_pk_bf16_f32 v10, v110, v20
	v_exp_f32_e32 v20, v15
	v_mul_f32_e32 v15, 0xbfb8aa3b, v17
	v_exp_f32_e32 v22, v15
	v_mul_f32_e32 v15, 0xbfb8aa3b, v18
	v_exp_f32_e32 v21, v15
	v_mov_b32_e32 v24, v6
	v_mov_b32_e32 v25, v8
	v_pk_mul_f32 v[24:25], v[24:25], v[14:15] op_sel_hi:[1,0]
	v_pk_add_f32 v[20:21], v[20:21], 1.0 op_sel_hi:[1,0]
	v_mov_b32_e32 v26, v106
	v_div_scale_f32 v6, s[8:9], v21, v21, v18
	v_rcp_f32_e32 v8, v6
	v_mov_b32_e32 v27, v108
	v_pk_mul_f32 v[24:25], v[24:25], v[26:27]
	v_mov_b32_e32 v108, v107
	v_fma_f32 v15, -v6, v8, 1.0
	v_fmac_f32_e32 v8, v15, v8
	v_div_scale_f32 v15, vcc, v18, v21, v18
	v_mul_f32_e32 v23, v15, v8
	v_fma_f32 v26, -v6, v23, v15
	v_fmac_f32_e32 v23, v26, v8
	v_fma_f32 v6, -v6, v23, v15
	v_div_scale_f32 v15, s[8:9], v20, v20, v16
	v_rcp_f32_e32 v26, v15
	v_div_fmas_f32 v6, v6, v8, v23
	v_div_fixup_f32 v21, v6, v21, v18
	v_fma_f32 v6, -v15, v26, 1.0
	v_fmac_f32_e32 v26, v6, v26
	v_div_scale_f32 v6, vcc, v16, v20, v16
	v_mul_f32_e32 v8, v6, v26
	v_fma_f32 v18, -v15, v8, v6
	v_fmac_f32_e32 v8, v18, v26
	v_fma_f32 v6, -v15, v8, v6
	v_div_fmas_f32 v6, v6, v26, v8
	v_mul_f32_e32 v8, 0xbfb8aa3b, v19
	v_exp_f32_e32 v23, v8
	v_div_fixup_f32 v20, v6, v20, v16
	v_mov_b32_e32 v8, v7
	v_pk_mul_f32 v[20:21], v[24:25], v[20:21]
	v_pk_add_f32 v[6:7], v[22:23], 1.0 op_sel_hi:[1,0]
	s_nop 0
	v_div_scale_f32 v15, s[8:9], v7, v7, v19
	v_rcp_f32_e32 v16, v15
	v_pk_mul_f32 v[8:9], v[8:9], v[14:15] op_sel_hi:[1,0]
	v_fma_f32 v18, -v15, v16, 1.0
	v_fmac_f32_e32 v16, v18, v16
	v_div_scale_f32 v18, vcc, v19, v7, v19
	v_mul_f32_e32 v22, v18, v16
	v_fma_f32 v23, -v15, v22, v18
	v_fmac_f32_e32 v22, v23, v16
	v_fma_f32 v15, -v15, v22, v18
	v_div_scale_f32 v18, s[8:9], v6, v6, v17
	v_rcp_f32_e32 v23, v18
	v_div_fmas_f32 v15, v15, v16, v22
	v_div_fixup_f32 v7, v15, v7, v19
	v_pk_mul_f32 v[8:9], v[8:9], v[108:109]
	v_fma_f32 v15, -v18, v23, 1.0
	v_fmac_f32_e32 v23, v15, v23
	v_div_scale_f32 v15, vcc, v17, v6, v17
	v_mul_f32_e32 v16, v15, v23
	v_fma_f32 v19, -v18, v16, v15
	v_fmac_f32_e32 v16, v19, v23
	v_fma_f32 v15, -v18, v16, v15
	v_div_fmas_f32 v15, v15, v23, v16
	v_div_fixup_f32 v6, v15, v6, v17
	v_pk_mul_f32 v[6:7], v[8:9], v[6:7]
	v_mul_f32_e32 v9, 0xbfb8aa3b, v35
	v_mul_f32_e32 v8, 0xbfb8aa3b, v34
	v_exp_f32_e32 v16, v9
	v_mul_f32_e32 v9, 0xbfb8aa3b, v36
	v_exp_f32_e32 v8, v8
	v_exp_f32_e32 v9, v9
	v_mov_b32_e32 v18, v2
	v_mov_b32_e32 v19, v4
	v_pk_mul_f32 v[18:19], v[18:19], v[14:15] op_sel_hi:[1,0]
	v_pk_add_f32 v[8:9], v[8:9], 1.0 op_sel_hi:[1,0]
	v_mov_b32_e32 v22, v38
	v_div_scale_f32 v2, s[8:9], v9, v9, v36
	v_rcp_f32_e32 v4, v2
	v_mov_b32_e32 v23, v40
	v_pk_mul_f32 v[18:19], v[18:19], v[22:23]
	v_mov_b32_e32 v40, v39
	v_fma_f32 v15, -v2, v4, 1.0
	v_fmac_f32_e32 v4, v15, v4
	v_div_scale_f32 v15, vcc, v36, v9, v36
	v_mul_f32_e32 v17, v15, v4
	v_fma_f32 v22, -v2, v17, v15
	v_fmac_f32_e32 v17, v22, v4
	v_fma_f32 v2, -v2, v17, v15
	v_div_scale_f32 v15, s[8:9], v8, v8, v34
	v_rcp_f32_e32 v22, v15
	v_div_fmas_f32 v2, v2, v4, v17
	v_div_fixup_f32 v9, v2, v9, v36
	v_fma_f32 v2, -v15, v22, 1.0
	v_fmac_f32_e32 v22, v2, v22
	v_div_scale_f32 v2, vcc, v34, v8, v34
	v_mul_f32_e32 v4, v2, v22
	v_fma_f32 v17, -v15, v4, v2
	v_fmac_f32_e32 v4, v17, v22
	v_fma_f32 v2, -v15, v4, v2
	v_div_fmas_f32 v2, v2, v22, v4
	v_mul_f32_e32 v4, 0xbfb8aa3b, v37
	v_exp_f32_e32 v17, v4
	v_div_fixup_f32 v8, v2, v8, v34
	v_mov_b32_e32 v4, v3
	v_pk_mul_f32 v[8:9], v[18:19], v[8:9]
	v_pk_add_f32 v[2:3], v[16:17], 1.0 op_sel_hi:[1,0]
	s_nop 0
	v_div_scale_f32 v15, s[8:9], v3, v3, v37
	v_rcp_f32_e32 v16, v15
	v_pk_mul_f32 v[4:5], v[4:5], v[14:15] op_sel_hi:[1,0]
	v_fma_f32 v14, -v15, v16, 1.0
	v_fmac_f32_e32 v16, v14, v16
	v_div_scale_f32 v14, vcc, v37, v3, v37
	v_mul_f32_e32 v17, v14, v16
	v_fma_f32 v18, -v15, v17, v14
	v_fmac_f32_e32 v17, v18, v16
	v_fma_f32 v14, -v15, v17, v14
	v_div_scale_f32 v15, s[8:9], v2, v2, v35
	v_rcp_f32_e32 v18, v15
	v_div_fmas_f32 v14, v14, v16, v17
	v_div_fixup_f32 v3, v14, v3, v37
	v_pk_mul_f32 v[4:5], v[4:5], v[40:41]
	v_fma_f32 v14, -v15, v18, 1.0
	v_fmac_f32_e32 v18, v14, v18
	v_div_scale_f32 v14, vcc, v35, v2, v35
	v_mul_f32_e32 v16, v14, v18
	v_fma_f32 v17, -v15, v16, v14
	v_fmac_f32_e32 v16, v17, v18
	v_fma_f32 v14, -v15, v16, v14
	v_div_fmas_f32 v14, v14, v18, v16
	v_div_fixup_f32 v2, v14, v2, v35
	v_pk_mul_f32 v[2:3], v[4:5], v[2:3]
	v_bfe_u32 v5, v2, 16, 1
	v_add3_u32 v2, v2, v5, s33
	v_bfe_u32 v14, v8, 16, 1
	v_add3_u32 v8, v8, v14, s33
	v_lshrrev_b32_e32 v4, 16, v8
	v_cvt_pk_bf16_f32 v5, v9, v3
	v_and_or_b32 v4, v2, s34, v4
	v_cvt_pk_bf16_f32 v3, v21, v7
	v_cvt_pk_bf16_f32 v2, v20, v6
	v_lshlrev_b64 v[6:7], 11, v[60:61]
	v_lshl_add_u64 v[6:7], s[68:69], 0, v[6:7]
	v_lshl_add_u64 v[6:7], v[6:7], 0, s[70:71]
	v_lshl_add_u64 v[6:7], v[6:7], 0, v[42:43]
	v_lshl_add_u64 v[8:9], v[6:7], 0, s[74:75]
	v_add_co_u32_e32 v6, vcc, 0xdc00000, v6
	s_nop 1
	v_addc_co_u32_e32 v7, vcc, 0, v7, vcc
	global_store_dwordx4 v[6:7], v[10:13], off offset:1024
	global_store_dwordx4 v[8:9], v[2:5], off offset:16
	s_branch .LBB0_2949

.LBB0_4869:
	v_lshl_add_u64 v[10:11], s[38:39], 0, v[8:9]
	v_add_co_u32_e32 v14, vcc, 0x22400000, v10
	v_lshl_add_u64 v[12:13], s[38:39], 0, v[6:7]
	s_nop 0
	v_addc_co_u32_e32 v15, vcc, 0, v11, vcc
	v_add_co_u32_e32 v12, vcc, 0x26400000, v12
	global_load_dword v3, v[14:15], off nt
	s_nop 0
	v_addc_co_u32_e32 v13, vcc, 0, v13, vcc
	v_add_co_u32_e32 v14, vcc, 0x22408000, v10
	global_load_dword v5, v[12:13], off nt
	global_load_dword v40, v[12:13], off offset:256 nt
	global_load_dword v41, v[12:13], off offset:512 nt
	global_load_dword v42, v[12:13], off offset:768 nt
	global_load_dword v43, v[12:13], off offset:1024 nt
	global_load_dword v44, v[12:13], off offset:1280 nt
	global_load_dword v45, v[12:13], off offset:1536 nt
	global_load_dword v46, v[12:13], off offset:1792 nt
	global_load_dword v47, v[12:13], off offset:2048 nt
	global_load_dword v48, v[12:13], off offset:2304 nt
	global_load_dword v49, v[12:13], off offset:2560 nt
	global_load_dword v50, v[12:13], off offset:2816 nt
	global_load_dword v51, v[12:13], off offset:3072 nt
	global_load_dword v52, v[12:13], off offset:3328 nt
	global_load_dword v53, v[12:13], off offset:3584 nt
	v_addc_co_u32_e32 v15, vcc, 0, v11, vcc
	v_add_co_u32_e32 v16, vcc, 0x22410000, v10
	s_add_i32 s2, s2, 16
	s_nop 0
	v_addc_co_u32_e32 v17, vcc, 0, v11, vcc
	v_add_co_u32_e32 v18, vcc, 0x22418000, v10
	global_load_dword v54, v[14:15], off nt
	global_load_dword v55, v[16:17], off nt
	v_addc_co_u32_e32 v19, vcc, 0, v11, vcc
	v_add_co_u32_e32 v14, vcc, 0x22420000, v10
	v_lshl_add_u64 v[6:7], v[6:7], 0, s[8:9]
	s_nop 0
	v_addc_co_u32_e32 v15, vcc, 0, v11, vcc
	v_add_co_u32_e32 v16, vcc, 0x22428000, v10
	global_load_dword v56, v[18:19], off nt
	global_load_dword v57, v[14:15], off nt
	v_addc_co_u32_e32 v17, vcc, 0, v11, vcc
	v_add_co_u32_e32 v14, vcc, 0x22430000, v10
	v_lshl_add_u64 v[8:9], v[8:9], 0, s[10:11]
	s_nop 0
	v_addc_co_u32_e32 v15, vcc, 0, v11, vcc
	v_add_co_u32_e32 v18, vcc, 0x22438000, v10
	global_load_dword v58, v[16:17], off nt
	global_load_dword v59, v[14:15], off nt
	v_addc_co_u32_e32 v19, vcc, 0, v11, vcc
	v_add_co_u32_e32 v14, vcc, 0x22440000, v10
	global_load_dword v60, v[18:19], off nt
	global_load_dword v61, v[12:13], off offset:3840 nt
	v_addc_co_u32_e32 v15, vcc, 0, v11, vcc
	v_add_co_u32_e32 v16, vcc, 0x22448000, v10
	s_cmpk_lt_u32 s2, 0x70
	s_nop 0
	v_addc_co_u32_e32 v17, vcc, 0, v11, vcc
	v_add_co_u32_e32 v12, vcc, 0x22450000, v10
	global_load_dword v62, v[14:15], off nt
	global_load_dword v63, v[16:17], off nt
	v_addc_co_u32_e32 v13, vcc, 0, v11, vcc
	v_add_co_u32_e32 v14, vcc, 0x22458000, v10
	s_waitcnt vmcnt(0) lgkmcnt(0)
	v_fmac_f32_e32 v3, v1, v5
	v_addc_co_u32_e32 v15, vcc, 0, v11, vcc
	v_add_co_u32_e32 v16, vcc, 0x22460000, v10
	global_load_dword v64, v[12:13], off nt
	global_load_dword v65, v[14:15], off nt
	v_addc_co_u32_e32 v17, vcc, 0, v11, vcc
	v_add_co_u32_e32 v12, vcc, 0x22468000, v10
	v_fmac_f32_e32 v54, v3, v40
	s_nop 0
	v_addc_co_u32_e32 v13, vcc, 0, v11, vcc
	v_add_co_u32_e32 v14, vcc, 0x22470000, v10
	global_load_dword v66, v[16:17], off nt
	global_load_dword v67, v[12:13], off nt
	v_addc_co_u32_e32 v15, vcc, 0, v11, vcc
	v_add_co_u32_e32 v12, vcc, 0x22478000, v10
	v_fmac_f32_e32 v55, v54, v41
	s_nop 0
	v_addc_co_u32_e32 v13, vcc, 0, v11, vcc
	global_load_dword v68, v[14:15], off nt
	global_load_dword v69, v[12:13], off nt
	v_add_co_u32_e32 v16, vcc, 0x24400000, v10
	v_fmac_f32_e32 v56, v55, v42
	s_nop 0
	v_addc_co_u32_e32 v17, vcc, 0, v11, vcc
	v_add_co_u32_e32 v12, vcc, 0x24408000, v10
	global_store_dword v[16:17], v1, off
	s_nop 0
	v_addc_co_u32_e32 v13, vcc, 0, v11, vcc
	v_add_co_u32_e32 v14, vcc, 0x24410000, v10
	v_fmac_f32_e32 v57, v56, v43
	s_nop 0
	v_addc_co_u32_e32 v15, vcc, 0, v11, vcc
	v_add_co_u32_e32 v16, vcc, 0x24418000, v10
	v_fmac_f32_e32 v58, v57, v44
	s_nop 0
	v_addc_co_u32_e32 v17, vcc, 0, v11, vcc
	v_add_co_u32_e32 v18, vcc, 0x24420000, v10
	v_fmac_f32_e32 v59, v58, v45
	s_nop 0
	v_addc_co_u32_e32 v19, vcc, 0, v11, vcc
	v_add_co_u32_e32 v20, vcc, 0x24428000, v10
	v_fmac_f32_e32 v60, v59, v46
	s_nop 0
	v_addc_co_u32_e32 v21, vcc, 0, v11, vcc
	v_add_co_u32_e32 v22, vcc, 0x24430000, v10
	v_fmac_f32_e32 v62, v60, v47
	s_nop 0
	v_addc_co_u32_e32 v23, vcc, 0, v11, vcc
	v_add_co_u32_e32 v24, vcc, 0x24438000, v10
	v_fmac_f32_e32 v63, v62, v48
	s_nop 0
	v_addc_co_u32_e32 v25, vcc, 0, v11, vcc
	v_add_co_u32_e32 v26, vcc, 0x24440000, v10
	global_store_dword v[12:13], v3, off
	s_nop 0
	v_addc_co_u32_e32 v27, vcc, 0, v11, vcc
	v_add_co_u32_e32 v28, vcc, 0x24448000, v10
	global_store_dword v[14:15], v54, off
	s_nop 0
	v_addc_co_u32_e32 v29, vcc, 0, v11, vcc
	v_add_co_u32_e32 v30, vcc, 0x24450000, v10
	global_store_dword v[16:17], v55, off
	s_nop 0
	v_addc_co_u32_e32 v31, vcc, 0, v11, vcc
	v_add_co_u32_e32 v32, vcc, 0x24458000, v10
	s_waitcnt vmcnt(0) lgkmcnt(0)
	v_fmac_f32_e32 v64, v63, v49
	v_addc_co_u32_e32 v33, vcc, 0, v11, vcc
	v_add_co_u32_e32 v34, vcc, 0x24460000, v10
	v_fmac_f32_e32 v65, v64, v50
	s_nop 0
	v_addc_co_u32_e32 v35, vcc, 0, v11, vcc
	v_add_co_u32_e32 v36, vcc, 0x24468000, v10
	global_store_dword v[18:19], v56, off
	s_nop 0
	v_addc_co_u32_e32 v37, vcc, 0, v11, vcc
	v_add_co_u32_e32 v38, vcc, 0x24470000, v10
	v_fmac_f32_e32 v66, v65, v51
	s_nop 0
	v_addc_co_u32_e32 v39, vcc, 0, v11, vcc
	v_fmac_f32_e32 v67, v66, v52
	v_add_co_u32_e32 v10, vcc, 0x24478000, v10
	v_fmac_f32_e32 v68, v67, v53
	v_mov_b32_e32 v1, v69
	v_addc_co_u32_e32 v11, vcc, 0, v11, vcc
	v_fmac_f32_e32 v1, v68, v61
	global_store_dword v[20:21], v57, off
	global_store_dword v[22:23], v58, off
	global_store_dword v[24:25], v59, off
	global_store_dword v[26:27], v60, off
	global_store_dword v[28:29], v62, off
	global_store_dword v[30:31], v63, off
	global_store_dword v[32:33], v64, off
	global_store_dword v[34:35], v65, off
	global_store_dword v[36:37], v66, off
	global_store_dword v[38:39], v67, off
	global_store_dword v[10:11], v68, off
	s_cbranch_scc1 .LBB0_4869
	v_ashrrev_i32_e32 v5, 31, v4
	v_readlane_b32 s2, v228, 15
	v_lshlrev_b64 v[4:5], 15, v[4:5]
	v_readlane_b32 s3, v228, 16
	v_lshlrev_b32_e32 v2, 2, v2
	v_mov_b32_e32 v3, 0
	v_lshl_add_u64 v[4:5], s[2:3], 0, v[4:5]
	v_lshl_add_u64 v[2:3], v[4:5], 0, v[2:3]
	v_add_co_u32_e32 v2, vcc, 0x82c0000, v2
	s_nop 1
	v_addc_co_u32_e32 v3, vcc, 0, v3, vcc
	global_store_dword v[2:3], v1, off

.LBB0_4890:
	s_and_b64 vcc, exec, s[6:7]
	s_cbranch_vccz .LBB0_5502
	s_add_u32 s5, s66, s83
	s_addc_u32 s6, s67, s82
	s_add_u32 s18, s5, 0x16000000
	s_movk_i32 s5, 0x100
	v_and_b32_e32 v1, 63, v138
	s_addc_u32 s19, s6, 0
	v_cmp_gt_i32_e32 vcc, s5, v138
	s_barrier
	s_and_saveexec_b64 s[6:7], vcc
	s_cbranch_execz .LBB0_4893
	v_and_b32_e32 v2, 0xffffffc0, v138
	v_readlane_b32 s5, v228, 21
	s_nop 1
	v_add_u32_e32 v2, s5, v2
	v_or_b32_e32 v2, v2, v1
	v_ashrrev_i32_e32 v3, 31, v2
	v_lshl_add_u64 v[2:3], v[2:3], 2, s[18:19]
	global_load_dword v2, v[2:3], off nt
	v_lshl_add_u32 v3, v138, 2, s3
	s_waitcnt vmcnt(0) lgkmcnt(0)
	v_mul_f32_e32 v2, 0x3e000000, v2
	ds_write_b32 v3, v2

.LBB0_4900:
	s_add_u32 s6, s66, s88
	s_addc_u32 s7, s67, s89
	s_lshl_b32 s52, s87, 2
	s_add_u32 s8, s6, s52
	s_addc_u32 s9, s7, 0
	v_lshlrev_b32_e32 v102, 2, v1
	v_mov_b32_e32 v103, v99
	s_lshl_b32 s6, s5, 4
	v_lshl_add_u64 v[2:3], s[8:9], 0, v[102:103]
	s_mov_b64 s[8:9], 0x6600000
	v_lshl_add_u64 v[2:3], v[2:3], 0, s[8:9]
	v_mov_b32_e32 v19, 0
	s_cmp_gt_i32 s5, 7
	v_mov_b32_e32 v10, 0
	s_waitcnt lgkmcnt(0)
	s_barrier
	s_cbranch_scc1 .LBB0_4902
	s_ashr_i32 s7, s6, 31
	s_lshl_b64 s[8:9], s[6:7], 9
	v_lshl_add_u64 v[4:5], v[2:3], 0, s[8:9]
	global_load_dword v10, v[4:5], off nt

.LBB0_5564:
	s_or_b64 exec, exec, s[76:77]
	s_lshl_b32 s9, s8, 4
	s_lshl_b32 s36, s8, 6
	s_and_b32 s9, s9, 0xffffe000
	s_and_b32 s36, s36, 0x1fc0
	s_or_b32 s36, s9, s36
	s_ashr_i32 s9, s8, 31
	s_bfe_u32 s35, s8, 0x20007
	s_lshl_b64 s[42:43], s[8:9], 14
	s_lshl_b32 s37, s35, 6
	v_add_u32_e32 v2, s36, v67
	v_mov_b64_e32 v[26:27], s[12:13]
	v_lshl_add_u64 v[4:5], v[56:57], 0, s[42:43]
	v_add_u32_e32 v10, s36, v68
	v_mad_i64_i32 v[2:3], s[44:45], v2, s29, v[26:27]
	v_add_lshl_u32 v42, v55, s37, 2
	v_add_lshl_u32 v8, v66, s37, 2
	v_mov_b32_e32 v9, v43
	v_mad_i64_i32 v[10:11], s[42:43], v10, s29, v[26:27]
	v_add_co_u32_e32 v14, vcc, s30, v4
	v_lshl_add_u64 v[6:7], v[2:3], 0, v[42:43]
	v_lshl_add_u64 v[2:3], v[2:3], 0, v[8:9]
	v_lshl_add_u64 v[12:13], v[10:11], 0, v[42:43]
	v_lshl_add_u64 v[10:11], v[10:11], 0, v[8:9]
	v_addc_co_u32_e32 v15, vcc, 0, v5, vcc
	global_load_dword v34, v[4:5], off nt
	global_load_dword v35, v[6:7], off nt
	global_load_dword v36, v[2:3], off nt
	global_load_dword v37, v[12:13], off nt
	global_load_dword v38, v[10:11], off nt
	global_load_dword v39, v[14:15], off nt
	global_load_dword v40, v[14:15], off offset:2048 nt
	global_load_dword v41, v[4:5], off offset:2048 nt
	v_add_u32_e32 v2, s36, v69
	v_mad_i64_i32 v[2:3], s[42:43], v2, s29, v[26:27]
	v_add_u32_e32 v10, s36, v70
	v_add_u32_e32 v14, s36, v71
	v_lshl_add_u64 v[6:7], v[2:3], 0, v[42:43]
	v_mad_i64_i32 v[10:11], s[42:43], v10, s29, v[26:27]
	v_mad_i64_i32 v[14:15], s[42:43], v14, s29, v[26:27]
	v_add_co_u32_e32 v16, vcc, s28, v4
	v_lshl_add_u64 v[2:3], v[2:3], 0, v[8:9]
	v_lshl_add_u64 v[12:13], v[10:11], 0, v[42:43]
	v_lshl_add_u64 v[10:11], v[10:11], 0, v[8:9]
	v_addc_co_u32_e32 v17, vcc, 0, v5, vcc
	v_lshl_add_u64 v[18:19], v[14:15], 0, v[42:43]
	v_lshl_add_u64 v[14:15], v[14:15], 0, v[8:9]
	global_load_dword v60, v[6:7], off nt
	global_load_dword v61, v[2:3], off nt
	global_load_dword v62, v[12:13], off nt
	global_load_dword v63, v[10:11], off nt
	global_load_dword v64, v[16:17], off nt
	global_load_dword v65, v[18:19], off nt
	global_load_dword v106, v[14:15], off nt
	global_load_dword v107, v[16:17], off offset:2048 nt
	v_add_u32_e32 v20, s36, v72
	v_mad_i64_i32 v[20:21], s[42:43], v20, s29, v[26:27]
	v_add_u32_e32 v10, s36, v73
	v_add_u32_e32 v14, s36, v74
	v_lshl_add_u64 v[2:3], v[20:21], 0, v[42:43]
	v_mad_i64_i32 v[10:11], s[42:43], v10, s29, v[26:27]
	v_add_co_u32_e32 v4, vcc, s29, v4
	v_mad_i64_i32 v[14:15], s[42:43], v14, s29, v[26:27]
	v_lshl_add_u64 v[6:7], v[20:21], 0, v[8:9]
	v_addc_co_u32_e32 v5, vcc, 0, v5, vcc
	v_lshl_add_u64 v[12:13], v[10:11], 0, v[42:43]
	v_lshl_add_u64 v[10:11], v[10:11], 0, v[8:9]
	v_lshl_add_u64 v[16:17], v[14:15], 0, v[42:43]
	v_lshl_add_u64 v[8:9], v[14:15], 0, v[8:9]
	global_load_dword v42, v[2:3], off nt
	global_load_dword v108, v[6:7], off nt
	global_load_dword v109, v[4:5], off nt
	global_load_dword v110, v[12:13], off nt
	global_load_dword v111, v[10:11], off nt
	global_load_dword v112, v[16:17], off nt
	global_load_dword v113, v[8:9], off nt
	global_load_dword v114, v[4:5], off offset:2048 nt
	s_lshl_b64 s[8:9], s[8:9], 15
	v_add_u32_e32 v2, s36, v75
	v_lshl_add_u64 v[28:29], v[44:45], 0, s[8:9]
	v_mad_i64_i32 v[2:3], s[8:9], v2, s29, v[26:27]
	s_lshl_b32 s70, s35, 9
	v_lshl_add_u64 v[2:3], v[2:3], 0, s[70:71]
	v_mov_b32_e32 v59, v43
	v_add_u32_e32 v10, s36, v76
	v_lshl_add_u64 v[2:3], v[2:3], 0, v[58:59]
	v_mad_i64_i32 v[10:11], s[8:9], v10, s29, v[26:27]
	v_add_co_u32_e32 v2, vcc, s30, v2
	v_lshl_add_u64 v[10:11], v[10:11], 0, s[70:71]
	v_add_u32_e32 v18, s36, v77
	v_addc_co_u32_e32 v3, vcc, 0, v3, vcc
	v_lshl_add_u64 v[10:11], v[10:11], 0, v[58:59]
	v_mad_i64_i32 v[18:19], s[8:9], v18, s29, v[26:27]
	v_add_co_u32_e32 v10, vcc, s30, v10
	v_lshl_add_u64 v[18:19], v[18:19], 0, s[70:71]
	v_add_u32_e32 v30, s36, v78
	v_addc_co_u32_e32 v11, vcc, 0, v11, vcc
	v_lshl_add_u64 v[18:19], v[18:19], 0, v[58:59]
	v_mad_i64_i32 v[26:27], s[8:9], v30, s29, v[26:27]
	v_add_co_u32_e32 v18, vcc, s30, v18
	v_lshl_add_u64 v[26:27], v[26:27], 0, s[70:71]
	s_nop 0
	v_addc_co_u32_e32 v19, vcc, 0, v19, vcc
	v_lshl_add_u64 v[26:27], v[26:27], 0, v[58:59]
	v_add_co_u32_e32 v26, vcc, s30, v26
	v_lshl_add_u64 v[6:7], v[46:47], 2, v[28:29]
	v_lshl_add_u64 v[14:15], v[48:49], 2, v[28:29]
	v_lshl_add_u64 v[22:23], v[50:51], 2, v[28:29]
	v_addc_co_u32_e32 v27, vcc, 0, v27, vcc
	v_lshl_add_u64 v[30:31], v[52:53], 2, v[28:29]
	global_load_dwordx4 v[2:5], v[2:3], off offset:3168 nt
	s_nop 0
	global_load_dwordx4 v[6:9], v[6:7], off nt
	s_nop 0
	global_load_dwordx4 v[10:13], v[10:11], off offset:3168 nt
	s_nop 0
	global_load_dwordx4 v[14:17], v[14:15], off nt
	s_nop 0
	global_load_dwordx4 v[18:21], v[18:19], off offset:3168 nt
	s_nop 0
	global_load_dwordx4 v[22:25], v[22:23], off nt
	s_nop 0
	global_load_dwordx4 v[26:29], v[26:27], off offset:3168 nt
	s_nop 0
	global_load_dwordx4 v[30:33], v[30:31], off nt
	s_waitcnt vmcnt(0) lgkmcnt(0)
	v_mul_f32_e32 v59, 0x3fb8aa3b, v34
	v_mul_f32_e32 v34, 0xbfb8aa3b, v34
	v_exp_f32_e32 v34, v34
	v_exp_f32_e32 v59, v59
	v_mul_f32_e32 v35, 0x3e000000, v35
	v_mul_f32_e32 v34, v36, v34
	v_mul_f32_e32 v36, 0x3fb8aa3b, v41
	v_exp_f32_e32 v36, v36
	v_mul_f32_e32 v35, v35, v59
	v_mul_f32_e32 v41, 0xbfb8aa3b, v41
	s_barrier
	v_exp_f32_e32 v41, v41
	ds_write2st64_b32 v79, v35, v34 offset0:65 offset1:130
	v_mul_f32_e32 v34, 0x3e000000, v37
	v_mul_f32_e32 v34, v34, v36
	v_mul_f32_e32 v36, 0x3fb8aa3b, v39
	v_mul_f32_e32 v37, 0xbfb8aa3b, v39
	v_exp_f32_e32 v36, v36
	v_exp_f32_e32 v37, v37
	v_mul_f32_e32 v35, v38, v41
	ds_write2st64_b32 v80, v34, v35 offset0:65 offset1:130
	v_mul_f32_e32 v34, 0x3e000000, v60
	v_mul_f32_e32 v34, v34, v36
	v_mul_f32_e32 v35, v61, v37
	v_mul_f32_e32 v36, 0x3fb8aa3b, v40
	v_mul_f32_e32 v37, 0xbfb8aa3b, v40
	v_exp_f32_e32 v36, v36
	v_exp_f32_e32 v37, v37
	ds_write2st64_b32 v81, v34, v35 offset0:65 offset1:130
	v_mul_f32_e32 v34, 0x3e000000, v62
	v_mul_f32_e32 v34, v34, v36
	v_mul_f32_e32 v35, v63, v37
	v_mul_f32_e32 v36, 0x3fb8aa3b, v64
	v_mul_f32_e32 v37, 0xbfb8aa3b, v64
	v_exp_f32_e32 v36, v36
	v_exp_f32_e32 v37, v37
	ds_write2st64_b32 v82, v34, v35 offset0:65 offset1:130
	v_mul_f32_e32 v34, 0x3e000000, v65
	v_mul_f32_e32 v34, v34, v36
	v_mul_f32_e32 v35, v106, v37
	v_mul_f32_e32 v36, 0x3fb8aa3b, v107
	v_mul_f32_e32 v37, 0xbfb8aa3b, v107
	v_exp_f32_e32 v36, v36
	v_exp_f32_e32 v37, v37
	ds_write2st64_b32 v83, v34, v35 offset0:65 offset1:130
	v_mul_f32_e32 v34, 0x3e000000, v42
	v_mul_f32_e32 v34, v34, v36
	v_mul_f32_e32 v35, v108, v37
	v_mul_f32_e32 v36, 0x3fb8aa3b, v109
	v_mul_f32_e32 v37, 0xbfb8aa3b, v109
	v_exp_f32_e32 v36, v36
	v_exp_f32_e32 v37, v37
	ds_write2st64_b32 v84, v34, v35 offset0:65 offset1:130
	v_mul_f32_e32 v34, 0x3e000000, v110
	v_mul_f32_e32 v34, v34, v36
	v_mul_f32_e32 v35, v111, v37
	v_mul_f32_e32 v36, 0x3fb8aa3b, v114
	v_mul_f32_e32 v37, 0xbfb8aa3b, v114
	v_exp_f32_e32 v36, v36
	v_exp_f32_e32 v37, v37
	ds_write2st64_b32 v85, v34, v35 offset0:65 offset1:130
	v_mul_f32_e32 v34, 0x3e000000, v112
	v_mul_f32_e32 v34, v34, v36
	v_mul_f32_e32 v35, v113, v37
	ds_write2st64_b32 v86, v34, v35 offset0:65 offset1:130
	ds_write_b128 v87, v[2:5] offset:49920
	ds_write_b128 v88, v[6:9]
	ds_write_b128 v87, v[10:13] offset:58112
	ds_write_b128 v89, v[14:17]
	ds_write_b128 v90, v[18:21]
	ds_write_b128 v91, v[22:25]
	ds_write_b128 v92, v[26:29]
	ds_write_b128 v93, v[30:33]
	v_mov_b32_e32 v2, 0
	s_lshl_b32 s35, s35, 7
	s_mov_b32 s8, 32
	v_mov_b32_e32 v18, v97
	v_mov_b32_e32 v19, v96
	v_mov_b32_e32 v3, v2
	v_mov_b32_e32 v4, v2
	v_mov_b32_e32 v5, v2
	v_mov_b32_e32 v6, v2
	v_mov_b32_e32 v7, v2
	v_mov_b32_e32 v8, v2
	v_mov_b32_e32 v9, v2
	v_mov_b32_e32 v10, v2
	v_mov_b32_e32 v11, v2
	v_mov_b32_e32 v12, v2
	v_mov_b32_e32 v13, v2
	v_mov_b32_e32 v14, v2
	v_mov_b32_e32 v15, v2
	v_mov_b32_e32 v16, v2
	v_mov_b32_e32 v17, v2
	s_waitcnt lgkmcnt(0)
	s_barrier

.LBB0_5572:
	ds_read2_b32 v[20:21], v18 offset1:2
	ds_read2st64_b32 v[22:23], v19 offset1:4
	s_add_i32 s8, s8, -8
	s_cmp_lg_u32 s8, 0
	s_waitcnt lgkmcnt(0)
	v_mfma_f32_32x32x2_f32 v[2:17], v20, v22, v[2:17]
	v_mfma_f32_32x32x2_f32 v[2:17], v21, v23, v[2:17]
	ds_read2_b32 v[20:21], v18 offset0:4 offset1:6
	ds_read2st64_b32 v[22:23], v19 offset0:8 offset1:12
	s_waitcnt lgkmcnt(0)
	v_mfma_f32_32x32x2_f32 v[2:17], v20, v22, v[2:17]
	v_mfma_f32_32x32x2_f32 v[2:17], v21, v23, v[2:17]
	ds_read2_b32 v[20:21], v18 offset0:8 offset1:10
	ds_read2st64_b32 v[22:23], v19 offset0:16 offset1:20
	s_waitcnt lgkmcnt(0)
	v_mfma_f32_32x32x2_f32 v[2:17], v20, v22, v[2:17]
	v_mfma_f32_32x32x2_f32 v[2:17], v21, v23, v[2:17]
	ds_read2_b32 v[20:21], v18 offset0:12 offset1:14
	ds_read2st64_b32 v[22:23], v19 offset0:24 offset1:28
	v_add_u32_e32 v19, 0x2000, v19
	v_add_u32_e32 v18, 64, v18
	s_waitcnt lgkmcnt(0)
	v_mfma_f32_32x32x2_f32 v[2:17], v20, v22, v[2:17]
	v_mfma_f32_32x32x2_f32 v[2:17], v21, v23, v[2:17]
	s_cbranch_scc1 .LBB0_5572
	v_add_u32_e32 v18, 0xc200, v103
	s_barrier
	s_nop 14
	ds_write2_b32 v18, v2, v3 offset0:64 offset1:196
	v_add_u32_e32 v2, 0xc600, v103
	ds_write2_b32 v2, v4, v5 offset0:72 offset1:204
	v_add_u32_e32 v2, 0xd200, v103
	ds_write2_b32 v2, v6, v7 offset0:96 offset1:228
	v_add_u32_e32 v2, 0xd600, v103
	ds_write2_b32 v2, v8, v9 offset0:104 offset1:236
	v_add_u32_e32 v2, 0xe400, v103
	ds_write2_b32 v2, v10, v11 offset1:132
	v_add_u32_e32 v2, 0xe800, v103
	ds_write2_b32 v2, v12, v13 offset0:8 offset1:140
	v_add_u32_e32 v2, 0xf400, v103
	ds_write2_b32 v2, v14, v15 offset0:32 offset1:164
	v_add_u32_e32 v2, 0xf800, v103
	v_mov_b64_e32 v[18:19], s[0:1]
	ds_write2_b32 v2, v16, v17 offset0:40 offset1:172
	s_waitcnt lgkmcnt(0)
	s_barrier
	ds_read_b128 v[14:17], v95 offset:49920
	ds_read_b128 v[10:13], v95 offset:49936
	ds_read_b128 v[6:9], v95 offset:49952
	ds_read_b128 v[2:5], v95 offset:49968
	global_load_dwordx2 v[22:23], v[18:19], off offset:168 sc0 sc1
	s_waitcnt vmcnt(0)
	v_add_u32_e32 v60, s36, v94
	v_mov_b64_e32 v[18:19], s[12:13]
	v_and_b32_e32 v21, 64, v166
	s_lshl_b32 s70, s35, 2
	v_mad_i64_i32 v[18:19], s[8:9], v60, s29, v[18:19]
	v_xor_b32_e32 v20, 1, v166
	v_lshlrev_b32_e32 v42, 2, v54
	v_add_u32_e32 v59, 64, v21
	v_lshl_add_u64 v[18:19], v[18:19], 0, s[70:71]
	v_cmp_lt_i32_e32 vcc, v20, v59
	v_lshl_add_u64 v[30:31], v[18:19], 0, v[42:43]
	s_waitcnt lgkmcnt(0)
	v_mov_b32_e32 v26, v15
	v_cndmask_b32_e32 v20, v166, v20, vcc
	v_add_co_u32_e32 v18, vcc, s28, v30
	v_lshlrev_b32_e32 v61, 2, v20
	s_nop 0
	v_addc_co_u32_e32 v19, vcc, 0, v31, vcc
	global_load_dwordx4 v[18:21], v[18:19], off offset:1184 nt
	v_mov_b32_e32 v27, v11
	v_mov_b32_e32 v24, v14
	v_mov_b32_e32 v25, v10
	v_mov_b32_e32 v36, v7
	v_mov_b32_e32 v37, v3
	v_pk_mul_f32 v[26:27], v[26:27], v[26:27]
	v_mov_b32_e32 v28, v16
	v_mov_b32_e32 v29, v12
	v_mov_b32_e32 v34, v6
	v_mov_b32_e32 v35, v2
	v_pk_mul_f32 v[36:37], v[36:37], v[36:37]
	v_pk_fma_f32 v[24:25], v[24:25], v[24:25], v[26:27]
	v_mov_b32_e32 v32, v17
	v_mov_b32_e32 v33, v13
	v_mov_b32_e32 v38, v8
	v_mov_b32_e32 v39, v4
	v_pk_fma_f32 v[26:27], v[34:35], v[34:35], v[36:37]
	v_pk_fma_f32 v[24:25], v[28:29], v[28:29], v[24:25]
	v_mov_b32_e32 v40, v9
	v_mov_b32_e32 v41, v5
	v_pk_fma_f32 v[26:27], v[38:39], v[38:39], v[26:27]
	v_pk_fma_f32 v[24:25], v[32:33], v[32:33], v[24:25]
	v_pk_fma_f32 v[26:27], v[40:41], v[40:41], v[26:27]
	v_add_f32_e32 v24, v24, v25
	v_add_f32_e32 v24, v24, v26
	v_add_f32_e32 v24, v24, v27
	ds_bpermute_b32 v25, v61, v24
	v_xor_b32_e32 v26, 2, v166
	v_cmp_lt_i32_e32 vcc, v26, v59
	v_lshl_add_u64 v[62:63], v[30:31], 0, s[72:73]
	v_mov_b32_e32 v38, v14
	v_cndmask_b32_e32 v26, v166, v26, vcc
	v_lshlrev_b32_e32 v26, 2, v26
	s_waitcnt lgkmcnt(0)
	v_add_f32_e32 v24, v24, v25
	ds_bpermute_b32 v25, v26, v24
	v_ashrrev_i32_e32 v61, 31, v60
	s_lshl_b32 s70, s35, 1
	s_mov_b64 s[76:77], 0
	s_waitcnt lgkmcnt(0)
	v_add_f32_e32 v32, v24, v25
	v_lshl_add_u64 v[64:65], v[22:23], 0, v[42:43]
	global_load_dwordx4 v[26:29], v[64:65], off offset:512 nt
	v_xor_b32_e32 v22, 4, v166
	v_cmp_lt_i32_e32 vcc, v22, v59
	s_nop 1
	v_cndmask_b32_e32 v22, v166, v22, vcc
	v_lshlrev_b32_e32 v22, 2, v22
	ds_bpermute_b32 v33, v22, v32
	global_load_dwordx4 v[22:25], v[64:65], off offset:528 nt
	s_waitcnt lgkmcnt(0)
	v_add_f32_e32 v30, v32, v33
	v_fmamk_f32 v30, v30, 0x3c000000, v104
	v_mul_f32_e32 v31, 0x4f800000, v30
	v_cmp_gt_f32_e32 vcc, s31, v30
	s_nop 1
	v_cndmask_b32_e32 v39, v30, v31, vcc
	v_sqrt_f32_e32 v40, v39
	global_load_dwordx4 v[30:33], v[62:63], off offset:16 nt
	global_load_dwordx4 v[34:37], v[62:63], off offset:48 nt
	v_add_u32_e32 v14, -1, v40
	v_add_u32_e32 v41, 1, v40
	v_fma_f32 v42, -v14, v40, v39
	v_fma_f32 v59, -v41, v40, v39
	v_cmp_ge_f32_e64 s[8:9], 0, v42
	s_nop 1
	v_cndmask_b32_e64 v14, v40, v14, s[8:9]
	v_cmp_lt_f32_e64 s[8:9], 0, v59
	s_nop 1
	v_cndmask_b32_e64 v14, v14, v41, s[8:9]
	v_mul_f32_e32 v40, 0x37800000, v14
	v_cndmask_b32_e32 v14, v14, v40, vcc
	v_cmp_class_f32_e32 vcc, v39, v105
	s_nop 1
	v_cndmask_b32_e32 v14, v14, v39, vcc
	v_div_scale_f32 v40, s[8:9], v14, v14, 1.0
	v_rcp_f32_e32 v41, v40
	v_mov_b32_e32 v39, v16
	v_div_scale_f32 v16, vcc, 1.0, v14, 1.0
	v_fma_f32 v42, -v40, v41, 1.0
	v_fmac_f32_e32 v41, v42, v41
	v_mul_f32_e32 v42, v16, v41
	v_fma_f32 v59, -v40, v42, v16
	v_fmac_f32_e32 v42, v59, v41
	v_fma_f32 v16, -v40, v42, v16
	v_div_fmas_f32 v16, v16, v41, v42
	v_div_fixup_f32 v14, v16, v14, 1.0
	v_pk_mul_f32 v[110:111], v[38:39], v[14:15] op_sel_hi:[1,0]
	s_waitcnt vmcnt(0)
	v_mul_f32_e32 v16, 0xbfb8aa3b, v18
	v_mul_f32_e32 v38, 0xbfb8aa3b, v20
	v_exp_f32_e32 v112, v16
	v_exp_f32_e32 v113, v38
	v_mul_f32_e32 v16, 0xbfb8aa3b, v19
	global_load_dwordx4 v[38:41], v[64:65], off offset:560 nt
	global_load_dwordx4 v[106:109], v[64:65], off offset:544 nt
	v_exp_f32_e32 v64, v16
	v_pk_add_f32 v[112:113], v[112:113], 1.0 op_sel_hi:[1,0]
	s_nop 0
	v_div_scale_f32 v16, s[8:9], v113, v113, v20
	v_rcp_f32_e32 v65, v16
	v_div_scale_f32 v59, s[8:9], v112, v112, v18
	v_rcp_f32_e32 v116, v59
	v_fma_f32 v114, -v16, v65, 1.0
	v_div_scale_f32 v42, vcc, v20, v113, v20
	v_fmac_f32_e32 v65, v114, v65
	v_fma_f32 v115, -v59, v116, 1.0
	v_mul_f32_e32 v114, v42, v65
	v_fmac_f32_e32 v116, v115, v116
	v_fma_f32 v115, -v16, v114, v42
	v_fmac_f32_e32 v114, v115, v65
	v_fma_f32 v16, -v16, v114, v42
	v_div_fmas_f32 v16, v16, v65, v114
	v_div_scale_f32 v117, s[8:9], v18, v112, v18
	v_div_fixup_f32 v113, v16, v113, v20
	v_mul_f32_e32 v20, 0xbfb8aa3b, v21
	v_mul_f32_e32 v118, v117, v116
	v_exp_f32_e32 v65, v20
	v_fma_f32 v119, -v59, v118, v117
	v_fmac_f32_e32 v118, v119, v116
	v_fma_f32 v16, -v59, v118, v117
	s_mov_b64 vcc, s[8:9]
	v_div_fmas_f32 v16, v16, v116, v118
	v_pk_add_f32 v[64:65], v[64:65], 1.0 op_sel_hi:[1,0]
	v_div_fixup_f32 v112, v16, v112, v18
	v_mov_b32_e32 v16, v15
	v_div_scale_f32 v15, s[8:9], v65, v65, v21
	v_rcp_f32_e32 v18, v15
	v_mov_b32_e32 v114, v26
	v_mov_b32_e32 v115, v28
	v_mov_b32_e32 v28, v27
	v_fma_f32 v20, -v15, v18, 1.0
	v_fmac_f32_e32 v18, v20, v18
	v_div_scale_f32 v20, vcc, v21, v65, v21
	v_mul_f32_e32 v26, v20, v18
	v_fma_f32 v27, -v15, v26, v20
	v_fmac_f32_e32 v26, v27, v18
	v_pk_mul_f32 v[16:17], v[16:17], v[14:15] op_sel_hi:[1,0]
	v_fma_f32 v15, -v15, v26, v20
	v_div_scale_f32 v20, s[8:9], v64, v64, v19
	v_rcp_f32_e32 v27, v20
	v_div_fmas_f32 v15, v15, v18, v26
	v_div_fixup_f32 v21, v15, v65, v21
	v_pk_mul_f32 v[16:17], v[28:29], v[16:17]
	v_fma_f32 v15, -v20, v27, 1.0
	v_fmac_f32_e32 v27, v15, v27
	v_div_scale_f32 v15, vcc, v19, v64, v19
	v_mul_f32_e32 v18, v15, v27
	v_fma_f32 v26, -v20, v18, v15
	v_fmac_f32_e32 v18, v26, v27
	v_fma_f32 v15, -v20, v18, v15
	v_div_fmas_f32 v15, v15, v27, v18
	v_div_fixup_f32 v20, v15, v64, v19
	v_pk_mul_f32 v[20:21], v[20:21], v[16:17]
	global_load_dwordx4 v[16:19], v[62:63], off offset:32 nt
	s_waitcnt lgkmcnt(0)
	v_mul_f32_e32 v15, 0xbfb8aa3b, v30
	v_exp_f32_e32 v26, v15
	v_mul_f32_e32 v15, 0xbfb8aa3b, v31
	v_exp_f32_e32 v28, v15
	v_mul_f32_e32 v15, 0xbfb8aa3b, v32
	v_exp_f32_e32 v27, v15
	v_mov_b32_e32 v62, v10
	v_mov_b32_e32 v63, v12
	v_pk_mul_f32 v[62:63], v[62:63], v[14:15] op_sel_hi:[1,0]
	v_pk_add_f32 v[26:27], v[26:27], 1.0 op_sel_hi:[1,0]
	v_mov_b32_e32 v64, v22
	v_div_scale_f32 v10, s[8:9], v27, v27, v32
	v_rcp_f32_e32 v12, v10
	v_mov_b32_e32 v65, v24
	v_pk_mul_f32 v[110:111], v[114:115], v[110:111]
	v_pk_mul_f32 v[62:63], v[62:63], v[64:65]
	v_fma_f32 v15, -v10, v12, 1.0
	v_fmac_f32_e32 v12, v15, v12
	v_div_scale_f32 v15, vcc, v32, v27, v32
	v_mul_f32_e32 v22, v15, v12
	v_fma_f32 v24, -v10, v22, v15
	v_fmac_f32_e32 v22, v24, v12
	v_fma_f32 v10, -v10, v22, v15
	v_div_scale_f32 v15, s[8:9], v26, v26, v30
	v_rcp_f32_e32 v24, v15
	v_div_fmas_f32 v10, v10, v12, v22
	v_div_fixup_f32 v27, v10, v27, v32
	v_pk_mul_f32 v[110:111], v[112:113], v[110:111]
	v_fma_f32 v10, -v15, v24, 1.0
	v_fmac_f32_e32 v24, v10, v24
	v_div_scale_f32 v10, vcc, v30, v26, v30
	v_mul_f32_e32 v12, v10, v24
	v_fma_f32 v22, -v15, v12, v10
	v_fmac_f32_e32 v12, v22, v24
	v_fma_f32 v10, -v15, v12, v10
	v_div_fmas_f32 v10, v10, v24, v12
	v_mul_f32_e32 v12, 0xbfb8aa3b, v33
	v_exp_f32_e32 v29, v12
	v_div_fixup_f32 v26, v10, v26, v30
	v_mov_b32_e32 v12, v11
	v_mov_b32_e32 v24, v23
	v_pk_add_f32 v[10:11], v[28:29], 1.0 op_sel_hi:[1,0]
	v_pk_mul_f32 v[26:27], v[62:63], v[26:27]
	v_div_scale_f32 v15, s[8:9], v11, v11, v33
	v_rcp_f32_e32 v22, v15
	v_pk_mul_f32 v[12:13], v[12:13], v[14:15] op_sel_hi:[1,0]
	v_lshlrev_b32_e32 v42, 1, v54
	v_pk_mul_f32 v[12:13], v[12:13], v[24:25]
	v_fma_f32 v23, -v15, v22, 1.0
	v_fmac_f32_e32 v22, v23, v22
	v_div_scale_f32 v23, vcc, v33, v11, v33
	v_mul_f32_e32 v24, v23, v22
	v_fma_f32 v25, -v15, v24, v23
	v_fmac_f32_e32 v24, v25, v22
	v_fma_f32 v15, -v15, v24, v23
	v_div_scale_f32 v23, s[8:9], v10, v10, v31
	v_rcp_f32_e32 v25, v23
	v_div_fmas_f32 v15, v15, v22, v24
	v_div_fixup_f32 v11, v15, v11, v33
	v_fma_f32 v15, -v23, v25, 1.0
	v_fmac_f32_e32 v25, v15, v25
	v_div_scale_f32 v15, vcc, v31, v10, v31
	v_mul_f32_e32 v22, v15, v25
	v_fma_f32 v24, -v23, v22, v15
	v_fmac_f32_e32 v22, v24, v25
	v_fma_f32 v15, -v23, v22, v15
	v_div_fmas_f32 v15, v15, v25, v22
	v_div_fixup_f32 v10, v15, v10, v31
	v_pk_mul_f32 v[10:11], v[12:13], v[10:11]
	v_cvt_pk_bf16_f32 v13, v27, v11
	v_cvt_pk_bf16_f32 v11, v111, v21
	s_waitcnt vmcnt(0)
	v_mul_f32_e32 v15, 0xbfb8aa3b, v16
	v_cvt_pk_bf16_f32 v12, v26, v10
	v_cvt_pk_bf16_f32 v10, v110, v20
	v_exp_f32_e32 v20, v15
	v_mul_f32_e32 v15, 0xbfb8aa3b, v17
	v_exp_f32_e32 v22, v15
	v_mul_f32_e32 v15, 0xbfb8aa3b, v18
	v_exp_f32_e32 v21, v15
	v_mov_b32_e32 v24, v6
	v_mov_b32_e32 v25, v8
	v_pk_mul_f32 v[24:25], v[24:25], v[14:15] op_sel_hi:[1,0]
	v_pk_add_f32 v[20:21], v[20:21], 1.0 op_sel_hi:[1,0]
	v_mov_b32_e32 v26, v106
	v_div_scale_f32 v6, s[8:9], v21, v21, v18
	v_rcp_f32_e32 v8, v6
	v_mov_b32_e32 v27, v108
	v_pk_mul_f32 v[24:25], v[24:25], v[26:27]
	v_mov_b32_e32 v108, v107
	v_fma_f32 v15, -v6, v8, 1.0
	v_fmac_f32_e32 v8, v15, v8
	v_div_scale_f32 v15, vcc, v18, v21, v18
	v_mul_f32_e32 v23, v15, v8
	v_fma_f32 v26, -v6, v23, v15
	v_fmac_f32_e32 v23, v26, v8
	v_fma_f32 v6, -v6, v23, v15
	v_div_scale_f32 v15, s[8:9], v20, v20, v16
	v_rcp_f32_e32 v26, v15
	v_div_fmas_f32 v6, v6, v8, v23
	v_div_fixup_f32 v21, v6, v21, v18
	v_fma_f32 v6, -v15, v26, 1.0
	v_fmac_f32_e32 v26, v6, v26
	v_div_scale_f32 v6, vcc, v16, v20, v16
	v_mul_f32_e32 v8, v6, v26
	v_fma_f32 v18, -v15, v8, v6
	v_fmac_f32_e32 v8, v18, v26
	v_fma_f32 v6, -v15, v8, v6
	v_div_fmas_f32 v6, v6, v26, v8
	v_mul_f32_e32 v8, 0xbfb8aa3b, v19
	v_exp_f32_e32 v23, v8
	v_div_fixup_f32 v20, v6, v20, v16
	v_mov_b32_e32 v8, v7
	v_pk_mul_f32 v[20:21], v[24:25], v[20:21]
	v_pk_add_f32 v[6:7], v[22:23], 1.0 op_sel_hi:[1,0]
	s_nop 0
	v_div_scale_f32 v15, s[8:9], v7, v7, v19
	v_rcp_f32_e32 v16, v15
	v_pk_mul_f32 v[8:9], v[8:9], v[14:15] op_sel_hi:[1,0]
	v_fma_f32 v18, -v15, v16, 1.0
	v_fmac_f32_e32 v16, v18, v16
	v_div_scale_f32 v18, vcc, v19, v7, v19
	v_mul_f32_e32 v22, v18, v16
	v_fma_f32 v23, -v15, v22, v18
	v_fmac_f32_e32 v22, v23, v16
	v_fma_f32 v15, -v15, v22, v18
	v_div_scale_f32 v18, s[8:9], v6, v6, v17
	v_rcp_f32_e32 v23, v18
	v_div_fmas_f32 v15, v15, v16, v22
	v_div_fixup_f32 v7, v15, v7, v19
	v_pk_mul_f32 v[8:9], v[8:9], v[108:109]
	v_fma_f32 v15, -v18, v23, 1.0
	v_fmac_f32_e32 v23, v15, v23
	v_div_scale_f32 v15, vcc, v17, v6, v17
	v_mul_f32_e32 v16, v15, v23
	v_fma_f32 v19, -v18, v16, v15
	v_fmac_f32_e32 v16, v19, v23
	v_fma_f32 v15, -v18, v16, v15
	v_div_fmas_f32 v15, v15, v23, v16
	v_div_fixup_f32 v6, v15, v6, v17
	v_pk_mul_f32 v[6:7], v[8:9], v[6:7]
	v_mul_f32_e32 v9, 0xbfb8aa3b, v35
	v_mul_f32_e32 v8, 0xbfb8aa3b, v34
	v_exp_f32_e32 v16, v9
	v_mul_f32_e32 v9, 0xbfb8aa3b, v36
	v_exp_f32_e32 v8, v8
	v_exp_f32_e32 v9, v9
	v_mov_b32_e32 v18, v2
	v_mov_b32_e32 v19, v4
	v_pk_mul_f32 v[18:19], v[18:19], v[14:15] op_sel_hi:[1,0]
	v_pk_add_f32 v[8:9], v[8:9], 1.0 op_sel_hi:[1,0]
	v_mov_b32_e32 v22, v38
	v_div_scale_f32 v2, s[8:9], v9, v9, v36
	v_rcp_f32_e32 v4, v2
	v_mov_b32_e32 v23, v40
	v_pk_mul_f32 v[18:19], v[18:19], v[22:23]
	v_mov_b32_e32 v40, v39
	v_fma_f32 v15, -v2, v4, 1.0
	v_fmac_f32_e32 v4, v15, v4
	v_div_scale_f32 v15, vcc, v36, v9, v36
	v_mul_f32_e32 v17, v15, v4
	v_fma_f32 v22, -v2, v17, v15
	v_fmac_f32_e32 v17, v22, v4
	v_fma_f32 v2, -v2, v17, v15
	v_div_scale_f32 v15, s[8:9], v8, v8, v34
	v_rcp_f32_e32 v22, v15
	v_div_fmas_f32 v2, v2, v4, v17
	v_div_fixup_f32 v9, v2, v9, v36
	v_fma_f32 v2, -v15, v22, 1.0
	v_fmac_f32_e32 v22, v2, v22
	v_div_scale_f32 v2, vcc, v34, v8, v34
	v_mul_f32_e32 v4, v2, v22
	v_fma_f32 v17, -v15, v4, v2
	v_fmac_f32_e32 v4, v17, v22
	v_fma_f32 v2, -v15, v4, v2
	v_div_fmas_f32 v2, v2, v22, v4
	v_mul_f32_e32 v4, 0xbfb8aa3b, v37
	v_exp_f32_e32 v17, v4
	v_div_fixup_f32 v8, v2, v8, v34
	v_mov_b32_e32 v4, v3
	v_pk_mul_f32 v[8:9], v[18:19], v[8:9]
	v_pk_add_f32 v[2:3], v[16:17], 1.0 op_sel_hi:[1,0]
	s_nop 0
	v_div_scale_f32 v15, s[8:9], v3, v3, v37
	v_rcp_f32_e32 v16, v15
	v_pk_mul_f32 v[4:5], v[4:5], v[14:15] op_sel_hi:[1,0]
	v_fma_f32 v14, -v15, v16, 1.0
	v_fmac_f32_e32 v16, v14, v16
	v_div_scale_f32 v14, vcc, v37, v3, v37
	v_mul_f32_e32 v17, v14, v16
	v_fma_f32 v18, -v15, v17, v14
	v_fmac_f32_e32 v17, v18, v16
	v_fma_f32 v14, -v15, v17, v14
	v_div_scale_f32 v15, s[8:9], v2, v2, v35
	v_rcp_f32_e32 v18, v15
	v_div_fmas_f32 v14, v14, v16, v17
	v_div_fixup_f32 v3, v14, v3, v37
	v_pk_mul_f32 v[4:5], v[4:5], v[40:41]
	v_fma_f32 v14, -v15, v18, 1.0
	v_fmac_f32_e32 v18, v14, v18
	v_div_scale_f32 v14, vcc, v35, v2, v35
	v_mul_f32_e32 v16, v14, v18
	v_fma_f32 v17, -v15, v16, v14
	v_fmac_f32_e32 v16, v17, v18
	v_fma_f32 v14, -v15, v16, v14
	v_div_fmas_f32 v14, v14, v18, v16
	v_div_fixup_f32 v2, v14, v2, v35
	v_pk_mul_f32 v[2:3], v[4:5], v[2:3]
	v_bfe_u32 v5, v2, 16, 1
	v_add3_u32 v2, v2, v5, s33
	v_bfe_u32 v14, v8, 16, 1
	v_add3_u32 v8, v8, v14, s33
	v_lshrrev_b32_e32 v4, 16, v8
	v_cvt_pk_bf16_f32 v5, v9, v3
	v_and_or_b32 v4, v2, s34, v4
	v_cvt_pk_bf16_f32 v3, v21, v7
	v_cvt_pk_bf16_f32 v2, v20, v6
	v_lshlrev_b64 v[6:7], 11, v[60:61]
	v_lshl_add_u64 v[6:7], s[68:69], 0, v[6:7]
	v_lshl_add_u64 v[6:7], v[6:7], 0, s[70:71]
	v_lshl_add_u64 v[6:7], v[6:7], 0, v[42:43]
	v_lshl_add_u64 v[8:9], v[6:7], 0, s[74:75]
	v_add_co_u32_e32 v6, vcc, 0xdc00000, v6
	s_nop 1
	v_addc_co_u32_e32 v7, vcc, 0, v7, vcc
	global_store_dwordx4 v[6:7], v[10:13], off offset:1024
	global_store_dwordx4 v[8:9], v[2:5], off offset:16
	s_branch .LBB0_5556
